# prep_item part A hand-written straight-line: 28 uniform head-vector jobs in 4 groups with batched loads (replaces divergent per-job branch chains)
# speedup vs baseline: 1.0209x; 1.0105x over previous
; DI void prep_item(const Params& p, int L, int item, char* smem) {
;   const int tid = TID();
;   const int b = item >> 5, s0 = (item & 31) * 64;
;   const size_t t0 = (size_t)b * S + s0;
;   const int sub = tid & 7;
; #pragma unroll 1
;   for (int jb = 0; jb < 44; jb += 4) {
;     u32x2 v0[4], v1[4];
; #pragma unroll
;     for (int u = 0; u < 4; ++u) {
;       const int job = (tid >> 3) + 32 * (jb + u);
;       const int tok = job & 63, vec = job >> 6;
;       int col;
;       if (vec < 4) col = 64 * vec; else if (vec < 8) col = 256 + 64 * (vec - 4); else if (vec < 12) col = 1964 + 64 * (vec - 8);
;       else if (vec < 16) col = 2220 + 64 * (vec - 12); else if (vec < 20) col = 1312 + 64 * (vec - 16); else if (vec == 20) col = 1696; else col = 1824;
;       const bfu* src = p.proj + (t0 + tok) * PJ + col + sub * 8;
;       v0[u] = *(const u32x2*)src; v1[u] = *(const u32x2*)(src + 4);
;     }
; #pragma unroll
;     for (int u = 0; u < 4; ++u) {
;       const int job = (tid >> 3) + 32 * (jb + u);
;       const int tok = job & 63, vec = job >> 6;
;       if ((vec < 8) ? (FUSE_MASK & 1) : (FUSE_MASK & 2)) continue;
;       const float* g = nullptr; float sc = 1.f; bfu* dst;
;       if (vec < 4)       { sc = 0.125f; dst = p.q_sb + (((size_t)(b * 4 + vec)) * S + s0 + tok) * 64; }
;       else if (vec < 8)  { int h = vec - 4; dst = p.k_sb + (((size_t)(b * 4 + h)) * S + s0 + tok) * 64; }
;       else if (vec < 12) { int h = vec - 8; g = p.fox_qn_g + L * 64; sc = 0.125f; dst = p.q_fox + (((size_t)(b * 4 + h)) * S + s0 + tok) * 64; }
;       else if (vec < 16) { int h = vec - 12; g = p.fox_kn_g + L * 64; dst = p.k_fox + (((size_t)(b * 4 + h)) * S + s0 + tok) * 64; }
;       else if (vec < 20) { int h = vec - 16; g = p.nsa_qn_g + L * 64; sc = 0.125f; dst = p.q_nsa + (((size_t)(b * 4 + h)) * S + s0 + tok) * 64; }
;       else if (vec == 20) { g = p.nsa_kn_g + (L * 3 + 1) * 64; dst = p.ks + ((size_t)b * S + s0 + tok) * 64; }
;       else               { g = p.nsa_kn_g + (L * 3 + 2) * 64; dst = p.kw + ((size_t)b * S + s0 + tok) * 64; }
;       float e[8] = {bflo(v0[u][0]), bfhi(v0[u][0]), bflo(v0[u][1]), bfhi(v0[u][1]), bflo(v1[u][0]), bfhi(v1[u][0]), bflo(v1[u][1]), bfhi(v1[u][1])};
;       float ss = 0.f;
; #pragma unroll
;       for (int q = 0; q < 8; ++q) ss += e[q] * e[q];
;       ss += __shfl_xor(ss, 1); ss += __shfl_xor(ss, 2); ss += __shfl_xor(ss, 4);
.LBB0_520:
	s_andn2_b64 vcc, exec, s[2:3]
	s_cbranch_vccnz .LBB0_751
	s_sub_i32 s2, s89, 24
	v_mov_b32_e32 v17, v224
	s_lshr_b32 s96, s2, 5
	s_lshl_b32 s2, s2, 6
	s_and_b32 s12, s2, 0x7c0
	s_lshl_b64 s[4:5], s[96:97], 11
	v_ashrrev_i32_e32 v29, 3, v17
	s_or_b32 s4, s4, s12
	v_and_b32_e32 v6, 63, v29
	v_bitop3_b32 v7, v29, 32, 63 bitop3:0x6c
	v_lshlrev_b32_e32 v27, 3, v17
	v_or_b32_e32 v0, s4, v6
	v_mov_b32_e32 v1, s5
	v_or_b32_e32 v2, s4, v7
	v_mov_b32_e32 v3, s5
	v_mov_b64_e32 v[4:5], s[68:69]
	v_and_b32_e32 v16, 56, v27
	v_lshlrev_b64 v[18:19], 7, v[0:1]
	v_lshlrev_b64 v[20:21], 7, v[2:3]
	v_mad_u64_u32 v[0:1], s[2:3], v0, s1, v[4:5]
	v_mov_b32_e32 v3, 0x1580
	v_mad_u32_u24 v1, s5, v3, v1
	v_lshlrev_b32_e32 v188, 1, v16
	v_lshl_add_u64 v[22:23], v[0:1], 0, v[188:189]
	v_mad_u64_u32 v[0:1], s[2:3], v2, s1, v[4:5]
	v_writelane_b32 v255, s11, 38
	s_mov_b32 s11, s35
	s_lshl_b32 s35, s96, 2
	v_mad_u32_u24 v1, s5, v3, v1
	s_mov_b64 s[92:93], s[84:85]
	s_add_i32 s94, s35, -16
	s_add_i32 s95, s35, -12
	s_add_i32 s15, s35, -8
	v_lshl_add_u64 v[24:25], v[0:1], 0, v[188:189]
	v_or_b32_e32 v26, s12, v6
	v_or_b32_e32 v28, s12, v7
	s_mov_b32 s14, 12
	v_add_u32_e32 v29, 0x200, v29
	v_readlane_b32 s52, v254, 38
	v_readlane_b32 s53, v254, 39
	v_readlane_b32 s2, v255, 26
	s_nop 3
	s_sub_u32 s52, s52, 0x288
	s_subb_u32 s53, s53, 0
	s_load_dwordx2 s[54:55], s[52:53], 0xa0
	s_load_dwordx2 s[56:57], s[52:53], 0xa8
	s_load_dwordx2 s[58:59], s[52:53], 0x88
	s_load_dwordx2 s[60:61], s[52:53], 0x90
	s_load_dwordx2 s[62:63], s[52:53], 0x1f0
	s_load_dwordx2 s[64:65], s[52:53], 0x1f8
	s_load_dwordx2 s[66:67], s[52:53], 0x208
	s_load_dwordx2 s[6:7], s[52:53], 0x210
	s_load_dwordx2 s[8:9], s[52:53], 0x220
	s_lshl_b32 s3, s2, 8
	s_mulk_i32 s2, 0x300
	s_addk_i32 s2, 0x100
	s_lshl_b32 s22, s35, 18
	s_lshl_b32 s23, s96, 18
	s_mov_b32 s24, 0x800000
	s_waitcnt lgkmcnt(0)
	s_add_u32 s54, s54, s3
	s_addc_u32 s55, s55, 0
	s_add_u32 s56, s56, s3
	s_addc_u32 s57, s57, 0
	s_add_u32 s58, s58, s3
	s_addc_u32 s59, s59, 0
	s_add_u32 s60, s60, s2
	s_addc_u32 s61, s61, 0
	s_add_u32 s62, s62, s22
	s_addc_u32 s63, s63, 0
	s_add_u32 s64, s64, s22
	s_addc_u32 s65, s65, 0
	s_add_u32 s66, s66, s22
	s_addc_u32 s67, s67, 0
	s_add_u32 s6, s6, s23
	s_addc_u32 s7, s7, 0
	s_add_u32 s8, s8, s23
	s_addc_u32 s9, s9, 0
	s_mov_b64 s[2:3], 0xa40
	v_lshl_add_u64 v[30:31], v[22:23], 0, s[2:3]
	v_lshl_add_u64 v[32:33], v[24:25], 0, s[2:3]
	v_lshlrev_b32_e32 v36, 1, v16
	v_lshl_add_u32 v34, v26, 7, v36
	v_lshl_add_u32 v35, v28, 7, v36
	v_lshlrev_b32_e32 v36, 2, v16
	global_load_dwordx4 v[40:43], v36, s[54:55]
	global_load_dwordx4 v[44:47], v36, s[54:55] offset:16
	global_load_dwordx4 v[60:63], v[30:31], off offset:1304
	global_load_dwordx4 v[64:67], v[32:33], off offset:1304
	global_load_dwordx4 v[68:71], v[30:31], off offset:1432
	global_load_dwordx4 v[72:75], v[32:33], off offset:1432
	global_load_dwordx4 v[76:79], v[30:31], off offset:1560
	global_load_dwordx4 v[8:11], v[32:33], off offset:1560
	global_load_dwordx4 v[12:15], v[30:31], off offset:1688
	global_load_dwordx4 v[48:51], v[32:33], off offset:1688
	s_waitcnt vmcnt(0)
	v_lshlrev_b32_e32 v0, 16, v60
	v_and_b32_e32 v1, 0xffff0000, v60
	v_lshlrev_b32_e32 v2, 16, v61
	v_and_b32_e32 v3, 0xffff0000, v61
	v_lshlrev_b32_e32 v4, 16, v62
	v_and_b32_e32 v5, 0xffff0000, v62
	v_lshlrev_b32_e32 v6, 16, v63
	v_and_b32_e32 v7, 0xffff0000, v63
	v_mul_f32_e32 v37, v0, v0
	v_fmac_f32_e32 v37, v1, v1
	v_fmac_f32_e32 v37, v2, v2
	v_fmac_f32_e32 v37, v3, v3
	v_fmac_f32_e32 v37, v4, v4
	v_fmac_f32_e32 v37, v5, v5
	v_fmac_f32_e32 v37, v6, v6
	v_fmac_f32_e32 v37, v7, v7
	s_nop 1
	v_add_f32_dpp v37, v37, v37 quad_perm:[1,0,3,2] row_mask:0xf bank_mask:0xf
	s_nop 1
	v_add_f32_dpp v37, v37, v37 quad_perm:[2,3,0,1] row_mask:0xf bank_mask:0xf
	s_nop 1
	v_add_f32_dpp v37, v37, v37 row_half_mirror row_mask:0xf bank_mask:0xf
	v_fmamk_f32 v38, v37, 0x3c800000, v225
	s_nop 0
	v_cmp_gt_f32_e64 s[2:3], s24, v38
	v_mul_f32_e32 v39, 0x4b800000, v38
	s_nop 0
	v_cndmask_b32_e64 v38, v38, v39, s[2:3]
	v_rsq_f32_e32 v38, v38
	s_nop 0
	v_mul_f32_e32 v39, 0x45800000, v38
	v_cndmask_b32_e64 v38, v38, v39, s[2:3]
	v_mul_f32_e32 v38, 0x3e000000, v38
	v_pk_mul_f32 v[0:1], v[0:1], v[38:39] op_sel_hi:[1,0]
	v_pk_mul_f32 v[2:3], v[2:3], v[38:39] op_sel_hi:[1,0]
	v_pk_mul_f32 v[4:5], v[4:5], v[38:39] op_sel_hi:[1,0]
	v_pk_mul_f32 v[6:7], v[6:7], v[38:39] op_sel_hi:[1,0]
	v_pk_mul_f32 v[0:1], v[0:1], v[40:41]
	v_pk_mul_f32 v[2:3], v[2:3], v[42:43]
	v_pk_mul_f32 v[4:5], v[4:5], v[44:45]
	v_pk_mul_f32 v[6:7], v[6:7], v[46:47]
	s_nop 0
	v_cvt_pk_bf16_f32 v60, v0, v1
	v_cvt_pk_bf16_f32 v61, v2, v3
	v_cvt_pk_bf16_f32 v62, v4, v5
	v_cvt_pk_bf16_f32 v63, v6, v7
	global_store_dwordx4 v34, v[60:63], s[62:63]
	v_lshlrev_b32_e32 v0, 16, v64
	v_and_b32_e32 v1, 0xffff0000, v64
	v_lshlrev_b32_e32 v2, 16, v65
	v_and_b32_e32 v3, 0xffff0000, v65
	v_lshlrev_b32_e32 v4, 16, v66
	v_and_b32_e32 v5, 0xffff0000, v66
	v_lshlrev_b32_e32 v6, 16, v67
	v_and_b32_e32 v7, 0xffff0000, v67
	v_mul_f32_e32 v37, v0, v0
	v_fmac_f32_e32 v37, v1, v1
	v_fmac_f32_e32 v37, v2, v2
	v_fmac_f32_e32 v37, v3, v3
	v_fmac_f32_e32 v37, v4, v4
	v_fmac_f32_e32 v37, v5, v5
	v_fmac_f32_e32 v37, v6, v6
	v_fmac_f32_e32 v37, v7, v7
	s_nop 1
	v_add_f32_dpp v37, v37, v37 quad_perm:[1,0,3,2] row_mask:0xf bank_mask:0xf
	s_nop 1
	v_add_f32_dpp v37, v37, v37 quad_perm:[2,3,0,1] row_mask:0xf bank_mask:0xf
	s_nop 1
	v_add_f32_dpp v37, v37, v37 row_half_mirror row_mask:0xf bank_mask:0xf
	v_fmamk_f32 v38, v37, 0x3c800000, v225
	s_nop 0
	v_cmp_gt_f32_e64 s[2:3], s24, v38
	v_mul_f32_e32 v39, 0x4b800000, v38
	s_nop 0
	v_cndmask_b32_e64 v38, v38, v39, s[2:3]
; DI void prep_item(const Params& p, int L, int item, char* smem) {
;     ...
;   for (int jb = 0; jb < 44; jb += 4) {
;     u32x2 v0[4], v1[4];
; #pragma unroll
;     for (int u = 0; u < 4; ++u) {
;       const int job = (tid >> 3) + 32 * (jb + u);
;       const int tok = job & 63, vec = job >> 6;
;       int col;
;       if (vec < 4) col = 64 * vec; else if (vec < 8) col = 256 + 64 * (vec - 4); else if (vec < 12) col = 1964 + 64 * (vec - 8);
;       else if (vec < 16) col = 2220 + 64 * (vec - 12); else if (vec < 20) col = 1312 + 64 * (vec - 16); else if (vec == 20) col = 1696; else col = 1824;
;       const bfu* src = p.proj + (t0 + tok) * PJ + col + sub * 8;
;       v0[u] = *(const u32x2*)src; v1[u] = *(const u32x2*)(src + 4);
;     }
; #pragma unroll
;     for (int u = 0; u < 4; ++u) {
;       const int job = (tid >> 3) + 32 * (jb + u);
;       const int tok = job & 63, vec = job >> 6;
;       if ((vec < 8) ? (FUSE_MASK & 1) : (FUSE_MASK & 2)) continue;
;       const float* g = nullptr; float sc = 1.f; bfu* dst;
;       if (vec < 4)       { sc = 0.125f; dst = p.q_sb + (((size_t)(b * 4 + vec)) * S + s0 + tok) * 64; }
;       else if (vec < 8)  { int h = vec - 4; dst = p.k_sb + (((size_t)(b * 4 + h)) * S + s0 + tok) * 64; }
;       else if (vec < 12) { int h = vec - 8; g = p.fox_qn_g + L * 64; sc = 0.125f; dst = p.q_fox + (((size_t)(b * 4 + h)) * S + s0 + tok) * 64; }
;       else if (vec < 16) { int h = vec - 12; g = p.fox_kn_g + L * 64; dst = p.k_fox + (((size_t)(b * 4 + h)) * S + s0 + tok) * 64; }
;       else if (vec < 20) { int h = vec - 16; g = p.nsa_qn_g + L * 64; sc = 0.125f; dst = p.q_nsa + (((size_t)(b * 4 + h)) * S + s0 + tok) * 64; }
;       else if (vec == 20) { g = p.nsa_kn_g + (L * 3 + 1) * 64; dst = p.ks + ((size_t)b * S + s0 + tok) * 64; }
;       else               { g = p.nsa_kn_g + (L * 3 + 2) * 64; dst = p.kw + ((size_t)b * S + s0 + tok) * 64; }
;       float e[8] = {bflo(v0[u][0]), bfhi(v0[u][0]), bflo(v0[u][1]), bfhi(v0[u][1]), bflo(v1[u][0]), bfhi(v1[u][0]), bflo(v1[u][1]), bfhi(v1[u][1])};
;       float ss = 0.f;
; #pragma unroll
;       for (int q = 0; q < 8; ++q) ss += e[q] * e[q];
;       ss += __shfl_xor(ss, 1); ss += __shfl_xor(ss, 2); ss += __shfl_xor(ss, 4);
;       const float rs = g ? rsqrtf(ss * (1.f / 64.f) + EPS) * sc : sc;
; #pragma unroll
;       for (int q = 0; q < 8; ++q) e[q] = e[q] * rs * (g ? g[sub * 8 + q] : 1.f);
	v_rsq_f32_e32 v38, v38
	s_nop 0
	v_mul_f32_e32 v39, 0x45800000, v38
	v_cndmask_b32_e64 v38, v38, v39, s[2:3]
	v_mul_f32_e32 v38, 0x3e000000, v38
	v_pk_mul_f32 v[0:1], v[0:1], v[38:39] op_sel_hi:[1,0]
	v_pk_mul_f32 v[2:3], v[2:3], v[38:39] op_sel_hi:[1,0]
	v_pk_mul_f32 v[4:5], v[4:5], v[38:39] op_sel_hi:[1,0]
	v_pk_mul_f32 v[6:7], v[6:7], v[38:39] op_sel_hi:[1,0]
	v_pk_mul_f32 v[0:1], v[0:1], v[40:41]
	v_pk_mul_f32 v[2:3], v[2:3], v[42:43]
	v_pk_mul_f32 v[4:5], v[4:5], v[44:45]
	v_pk_mul_f32 v[6:7], v[6:7], v[46:47]
	s_nop 0
	v_cvt_pk_bf16_f32 v64, v0, v1
	v_cvt_pk_bf16_f32 v65, v2, v3
	v_cvt_pk_bf16_f32 v66, v4, v5
	v_cvt_pk_bf16_f32 v67, v6, v7
	global_store_dwordx4 v35, v[64:67], s[62:63]
	s_add_u32 s62, s62, 0x40000
	s_addc_u32 s63, s63, 0
	v_lshlrev_b32_e32 v0, 16, v68
	v_and_b32_e32 v1, 0xffff0000, v68
	v_lshlrev_b32_e32 v2, 16, v69
	v_and_b32_e32 v3, 0xffff0000, v69
	v_lshlrev_b32_e32 v4, 16, v70
	v_and_b32_e32 v5, 0xffff0000, v70
	v_lshlrev_b32_e32 v6, 16, v71
	v_and_b32_e32 v7, 0xffff0000, v71
	v_mul_f32_e32 v37, v0, v0
	v_fmac_f32_e32 v37, v1, v1
	v_fmac_f32_e32 v37, v2, v2
	v_fmac_f32_e32 v37, v3, v3
	v_fmac_f32_e32 v37, v4, v4
	v_fmac_f32_e32 v37, v5, v5
	v_fmac_f32_e32 v37, v6, v6
	v_fmac_f32_e32 v37, v7, v7
	s_nop 1
	v_add_f32_dpp v37, v37, v37 quad_perm:[1,0,3,2] row_mask:0xf bank_mask:0xf
	s_nop 1
	v_add_f32_dpp v37, v37, v37 quad_perm:[2,3,0,1] row_mask:0xf bank_mask:0xf
	s_nop 1
	v_add_f32_dpp v37, v37, v37 row_half_mirror row_mask:0xf bank_mask:0xf
	v_fmamk_f32 v38, v37, 0x3c800000, v225
	s_nop 0
	v_cmp_gt_f32_e64 s[2:3], s24, v38
	v_mul_f32_e32 v39, 0x4b800000, v38
	s_nop 0
	v_cndmask_b32_e64 v38, v38, v39, s[2:3]
	v_rsq_f32_e32 v38, v38
	s_nop 0
	v_mul_f32_e32 v39, 0x45800000, v38
	v_cndmask_b32_e64 v38, v38, v39, s[2:3]
	v_mul_f32_e32 v38, 0x3e000000, v38
	v_pk_mul_f32 v[0:1], v[0:1], v[38:39] op_sel_hi:[1,0]
	v_pk_mul_f32 v[2:3], v[2:3], v[38:39] op_sel_hi:[1,0]
	v_pk_mul_f32 v[4:5], v[4:5], v[38:39] op_sel_hi:[1,0]
	v_pk_mul_f32 v[6:7], v[6:7], v[38:39] op_sel_hi:[1,0]
	v_pk_mul_f32 v[0:1], v[0:1], v[40:41]
	v_pk_mul_f32 v[2:3], v[2:3], v[42:43]
	v_pk_mul_f32 v[4:5], v[4:5], v[44:45]
	v_pk_mul_f32 v[6:7], v[6:7], v[46:47]
	s_nop 0
	v_cvt_pk_bf16_f32 v68, v0, v1
	v_cvt_pk_bf16_f32 v69, v2, v3
	v_cvt_pk_bf16_f32 v70, v4, v5
	v_cvt_pk_bf16_f32 v71, v6, v7
	global_store_dwordx4 v34, v[68:71], s[62:63]
	v_lshlrev_b32_e32 v0, 16, v72
	v_and_b32_e32 v1, 0xffff0000, v72
	v_lshlrev_b32_e32 v2, 16, v73
	v_and_b32_e32 v3, 0xffff0000, v73
	v_lshlrev_b32_e32 v4, 16, v74
	v_and_b32_e32 v5, 0xffff0000, v74
	v_lshlrev_b32_e32 v6, 16, v75
	v_and_b32_e32 v7, 0xffff0000, v75
	v_mul_f32_e32 v37, v0, v0
	v_fmac_f32_e32 v37, v1, v1
	v_fmac_f32_e32 v37, v2, v2
	v_fmac_f32_e32 v37, v3, v3
	v_fmac_f32_e32 v37, v4, v4
	v_fmac_f32_e32 v37, v5, v5
	v_fmac_f32_e32 v37, v6, v6
	v_fmac_f32_e32 v37, v7, v7
	s_nop 1
	v_add_f32_dpp v37, v37, v37 quad_perm:[1,0,3,2] row_mask:0xf bank_mask:0xf
	s_nop 1
	v_add_f32_dpp v37, v37, v37 quad_perm:[2,3,0,1] row_mask:0xf bank_mask:0xf
	s_nop 1
	v_add_f32_dpp v37, v37, v37 row_half_mirror row_mask:0xf bank_mask:0xf
	v_fmamk_f32 v38, v37, 0x3c800000, v225
	s_nop 0
	v_cmp_gt_f32_e64 s[2:3], s24, v38
	v_mul_f32_e32 v39, 0x4b800000, v38
	s_nop 0
	v_cndmask_b32_e64 v38, v38, v39, s[2:3]
	v_rsq_f32_e32 v38, v38
	s_nop 0
	v_mul_f32_e32 v39, 0x45800000, v38
	v_cndmask_b32_e64 v38, v38, v39, s[2:3]
	v_mul_f32_e32 v38, 0x3e000000, v38
	v_pk_mul_f32 v[0:1], v[0:1], v[38:39] op_sel_hi:[1,0]
	v_pk_mul_f32 v[2:3], v[2:3], v[38:39] op_sel_hi:[1,0]
	v_pk_mul_f32 v[4:5], v[4:5], v[38:39] op_sel_hi:[1,0]
	v_pk_mul_f32 v[6:7], v[6:7], v[38:39] op_sel_hi:[1,0]
	v_pk_mul_f32 v[0:1], v[0:1], v[40:41]
	v_pk_mul_f32 v[2:3], v[2:3], v[42:43]
	v_pk_mul_f32 v[4:5], v[4:5], v[44:45]
	v_pk_mul_f32 v[6:7], v[6:7], v[46:47]
	s_nop 0
	v_cvt_pk_bf16_f32 v72, v0, v1
	v_cvt_pk_bf16_f32 v73, v2, v3
	v_cvt_pk_bf16_f32 v74, v4, v5
	v_cvt_pk_bf16_f32 v75, v6, v7
	global_store_dwordx4 v35, v[72:75], s[62:63]
	s_add_u32 s62, s62, 0x40000
	s_addc_u32 s63, s63, 0
	v_lshlrev_b32_e32 v0, 16, v76
	v_and_b32_e32 v1, 0xffff0000, v76
	v_lshlrev_b32_e32 v2, 16, v77
	v_and_b32_e32 v3, 0xffff0000, v77
	v_lshlrev_b32_e32 v4, 16, v78
	v_and_b32_e32 v5, 0xffff0000, v78
	v_lshlrev_b32_e32 v6, 16, v79
	v_and_b32_e32 v7, 0xffff0000, v79
	v_mul_f32_e32 v37, v0, v0
	v_fmac_f32_e32 v37, v1, v1
	v_fmac_f32_e32 v37, v2, v2
	v_fmac_f32_e32 v37, v3, v3
	v_fmac_f32_e32 v37, v4, v4
	v_fmac_f32_e32 v37, v5, v5
	v_fmac_f32_e32 v37, v6, v6
	v_fmac_f32_e32 v37, v7, v7
	s_nop 1
	v_add_f32_dpp v37, v37, v37 quad_perm:[1,0,3,2] row_mask:0xf bank_mask:0xf
	s_nop 1
	v_add_f32_dpp v37, v37, v37 quad_perm:[2,3,0,1] row_mask:0xf bank_mask:0xf
	s_nop 1
	v_add_f32_dpp v37, v37, v37 row_half_mirror row_mask:0xf bank_mask:0xf
	v_fmamk_f32 v38, v37, 0x3c800000, v225
	s_nop 0
	v_cmp_gt_f32_e64 s[2:3], s24, v38
	v_mul_f32_e32 v39, 0x4b800000, v38
	s_nop 0
	v_cndmask_b32_e64 v38, v38, v39, s[2:3]
	v_rsq_f32_e32 v38, v38
	s_nop 0
	v_mul_f32_e32 v39, 0x45800000, v38
	v_cndmask_b32_e64 v38, v38, v39, s[2:3]
	v_mul_f32_e32 v38, 0x3e000000, v38
	v_pk_mul_f32 v[0:1], v[0:1], v[38:39] op_sel_hi:[1,0]
	v_pk_mul_f32 v[2:3], v[2:3], v[38:39] op_sel_hi:[1,0]
	v_pk_mul_f32 v[4:5], v[4:5], v[38:39] op_sel_hi:[1,0]
	v_pk_mul_f32 v[6:7], v[6:7], v[38:39] op_sel_hi:[1,0]
	v_pk_mul_f32 v[0:1], v[0:1], v[40:41]
	v_pk_mul_f32 v[2:3], v[2:3], v[42:43]
	v_pk_mul_f32 v[4:5], v[4:5], v[44:45]
	v_pk_mul_f32 v[6:7], v[6:7], v[46:47]
	s_nop 0
	v_cvt_pk_bf16_f32 v76, v0, v1
	v_cvt_pk_bf16_f32 v77, v2, v3
	v_cvt_pk_bf16_f32 v78, v4, v5
	v_cvt_pk_bf16_f32 v79, v6, v7
	global_store_dwordx4 v34, v[76:79], s[62:63]
; DI void prep_item(const Params& p, int L, int item, char* smem) {
;     ...
;   for (int jb = 0; jb < 44; jb += 4) {
;     u32x2 v0[4], v1[4];
; #pragma unroll
;     for (int u = 0; u < 4; ++u) {
;       const int job = (tid >> 3) + 32 * (jb + u);
;       const int tok = job & 63, vec = job >> 6;
;       int col;
;       if (vec < 4) col = 64 * vec; else if (vec < 8) col = 256 + 64 * (vec - 4); else if (vec < 12) col = 1964 + 64 * (vec - 8);
;       else if (vec < 16) col = 2220 + 64 * (vec - 12); else if (vec < 20) col = 1312 + 64 * (vec - 16); else if (vec == 20) col = 1696; else col = 1824;
;       const bfu* src = p.proj + (t0 + tok) * PJ + col + sub * 8;
;       v0[u] = *(const u32x2*)src; v1[u] = *(const u32x2*)(src + 4);
;     }
; #pragma unroll
;     for (int u = 0; u < 4; ++u) {
;       const int job = (tid >> 3) + 32 * (jb + u);
;       const int tok = job & 63, vec = job >> 6;
;       if ((vec < 8) ? (FUSE_MASK & 1) : (FUSE_MASK & 2)) continue;
;       const float* g = nullptr; float sc = 1.f; bfu* dst;
;       if (vec < 4)       { sc = 0.125f; dst = p.q_sb + (((size_t)(b * 4 + vec)) * S + s0 + tok) * 64; }
;       else if (vec < 8)  { int h = vec - 4; dst = p.k_sb + (((size_t)(b * 4 + h)) * S + s0 + tok) * 64; }
;       else if (vec < 12) { int h = vec - 8; g = p.fox_qn_g + L * 64; sc = 0.125f; dst = p.q_fox + (((size_t)(b * 4 + h)) * S + s0 + tok) * 64; }
;       else if (vec < 16) { int h = vec - 12; g = p.fox_kn_g + L * 64; dst = p.k_fox + (((size_t)(b * 4 + h)) * S + s0 + tok) * 64; }
;       else if (vec < 20) { int h = vec - 16; g = p.nsa_qn_g + L * 64; sc = 0.125f; dst = p.q_nsa + (((size_t)(b * 4 + h)) * S + s0 + tok) * 64; }
;       else if (vec == 20) { g = p.nsa_kn_g + (L * 3 + 1) * 64; dst = p.ks + ((size_t)b * S + s0 + tok) * 64; }
;       else               { g = p.nsa_kn_g + (L * 3 + 2) * 64; dst = p.kw + ((size_t)b * S + s0 + tok) * 64; }
;       float e[8] = {bflo(v0[u][0]), bfhi(v0[u][0]), bflo(v0[u][1]), bfhi(v0[u][1]), bflo(v1[u][0]), bfhi(v1[u][0]), bflo(v1[u][1]), bfhi(v1[u][1])};
;       float ss = 0.f;
; #pragma unroll
;       for (int q = 0; q < 8; ++q) ss += e[q] * e[q];
;       ss += __shfl_xor(ss, 1); ss += __shfl_xor(ss, 2); ss += __shfl_xor(ss, 4);
;       const float rs = g ? rsqrtf(ss * (1.f / 64.f) + EPS) * sc : sc;
; #pragma unroll
;       for (int q = 0; q < 8; ++q) e[q] = e[q] * rs * (g ? g[sub * 8 + q] : 1.f);
	v_lshlrev_b32_e32 v0, 16, v8
	v_and_b32_e32 v1, 0xffff0000, v8
	v_lshlrev_b32_e32 v2, 16, v9
	v_and_b32_e32 v3, 0xffff0000, v9
	v_lshlrev_b32_e32 v4, 16, v10
	v_and_b32_e32 v5, 0xffff0000, v10
	v_lshlrev_b32_e32 v6, 16, v11
	v_and_b32_e32 v7, 0xffff0000, v11
	v_mul_f32_e32 v37, v0, v0
	v_fmac_f32_e32 v37, v1, v1
	v_fmac_f32_e32 v37, v2, v2
	v_fmac_f32_e32 v37, v3, v3
	v_fmac_f32_e32 v37, v4, v4
	v_fmac_f32_e32 v37, v5, v5
	v_fmac_f32_e32 v37, v6, v6
	v_fmac_f32_e32 v37, v7, v7
	s_nop 1
	v_add_f32_dpp v37, v37, v37 quad_perm:[1,0,3,2] row_mask:0xf bank_mask:0xf
	s_nop 1
	v_add_f32_dpp v37, v37, v37 quad_perm:[2,3,0,1] row_mask:0xf bank_mask:0xf
	s_nop 1
	v_add_f32_dpp v37, v37, v37 row_half_mirror row_mask:0xf bank_mask:0xf
	v_fmamk_f32 v38, v37, 0x3c800000, v225
	s_nop 0
	v_cmp_gt_f32_e64 s[2:3], s24, v38
	v_mul_f32_e32 v39, 0x4b800000, v38
	s_nop 0
	v_cndmask_b32_e64 v38, v38, v39, s[2:3]
	v_rsq_f32_e32 v38, v38
	s_nop 0
	v_mul_f32_e32 v39, 0x45800000, v38
	v_cndmask_b32_e64 v38, v38, v39, s[2:3]
	v_mul_f32_e32 v38, 0x3e000000, v38
	v_pk_mul_f32 v[0:1], v[0:1], v[38:39] op_sel_hi:[1,0]
	v_pk_mul_f32 v[2:3], v[2:3], v[38:39] op_sel_hi:[1,0]
	v_pk_mul_f32 v[4:5], v[4:5], v[38:39] op_sel_hi:[1,0]
	v_pk_mul_f32 v[6:7], v[6:7], v[38:39] op_sel_hi:[1,0]
	v_pk_mul_f32 v[0:1], v[0:1], v[40:41]
	v_pk_mul_f32 v[2:3], v[2:3], v[42:43]
	v_pk_mul_f32 v[4:5], v[4:5], v[44:45]
	v_pk_mul_f32 v[6:7], v[6:7], v[46:47]
	s_nop 0
	v_cvt_pk_bf16_f32 v8, v0, v1
	v_cvt_pk_bf16_f32 v9, v2, v3
	v_cvt_pk_bf16_f32 v10, v4, v5
	v_cvt_pk_bf16_f32 v11, v6, v7
	global_store_dwordx4 v35, v[8:11], s[62:63]
	s_add_u32 s62, s62, 0x40000
	s_addc_u32 s63, s63, 0
	v_lshlrev_b32_e32 v0, 16, v12
	v_and_b32_e32 v1, 0xffff0000, v12
	v_lshlrev_b32_e32 v2, 16, v13
	v_and_b32_e32 v3, 0xffff0000, v13
	v_lshlrev_b32_e32 v4, 16, v14
	v_and_b32_e32 v5, 0xffff0000, v14
	v_lshlrev_b32_e32 v6, 16, v15
	v_and_b32_e32 v7, 0xffff0000, v15
	v_mul_f32_e32 v37, v0, v0
	v_fmac_f32_e32 v37, v1, v1
	v_fmac_f32_e32 v37, v2, v2
	v_fmac_f32_e32 v37, v3, v3
	v_fmac_f32_e32 v37, v4, v4
	v_fmac_f32_e32 v37, v5, v5
	v_fmac_f32_e32 v37, v6, v6
	v_fmac_f32_e32 v37, v7, v7
	s_nop 1
	v_add_f32_dpp v37, v37, v37 quad_perm:[1,0,3,2] row_mask:0xf bank_mask:0xf
	s_nop 1
	v_add_f32_dpp v37, v37, v37 quad_perm:[2,3,0,1] row_mask:0xf bank_mask:0xf
	s_nop 1
	v_add_f32_dpp v37, v37, v37 row_half_mirror row_mask:0xf bank_mask:0xf
	v_fmamk_f32 v38, v37, 0x3c800000, v225
	s_nop 0
	v_cmp_gt_f32_e64 s[2:3], s24, v38
	v_mul_f32_e32 v39, 0x4b800000, v38
	s_nop 0
	v_cndmask_b32_e64 v38, v38, v39, s[2:3]
	v_rsq_f32_e32 v38, v38
	s_nop 0
	v_mul_f32_e32 v39, 0x45800000, v38
	v_cndmask_b32_e64 v38, v38, v39, s[2:3]
	v_mul_f32_e32 v38, 0x3e000000, v38
	v_pk_mul_f32 v[0:1], v[0:1], v[38:39] op_sel_hi:[1,0]
	v_pk_mul_f32 v[2:3], v[2:3], v[38:39] op_sel_hi:[1,0]
	v_pk_mul_f32 v[4:5], v[4:5], v[38:39] op_sel_hi:[1,0]
	v_pk_mul_f32 v[6:7], v[6:7], v[38:39] op_sel_hi:[1,0]
	v_pk_mul_f32 v[0:1], v[0:1], v[40:41]
	v_pk_mul_f32 v[2:3], v[2:3], v[42:43]
	v_pk_mul_f32 v[4:5], v[4:5], v[44:45]
	v_pk_mul_f32 v[6:7], v[6:7], v[46:47]
	s_nop 0
	v_cvt_pk_bf16_f32 v12, v0, v1
	v_cvt_pk_bf16_f32 v13, v2, v3
	v_cvt_pk_bf16_f32 v14, v4, v5
	v_cvt_pk_bf16_f32 v15, v6, v7
	global_store_dwordx4 v34, v[12:15], s[62:63]
	v_lshlrev_b32_e32 v0, 16, v48
	v_and_b32_e32 v1, 0xffff0000, v48
	v_lshlrev_b32_e32 v2, 16, v49
	v_and_b32_e32 v3, 0xffff0000, v49
	v_lshlrev_b32_e32 v4, 16, v50
	v_and_b32_e32 v5, 0xffff0000, v50
	v_lshlrev_b32_e32 v6, 16, v51
	v_and_b32_e32 v7, 0xffff0000, v51
	v_mul_f32_e32 v37, v0, v0
	v_fmac_f32_e32 v37, v1, v1
	v_fmac_f32_e32 v37, v2, v2
	v_fmac_f32_e32 v37, v3, v3
	v_fmac_f32_e32 v37, v4, v4
	v_fmac_f32_e32 v37, v5, v5
	v_fmac_f32_e32 v37, v6, v6
	v_fmac_f32_e32 v37, v7, v7
	s_nop 1
	v_add_f32_dpp v37, v37, v37 quad_perm:[1,0,3,2] row_mask:0xf bank_mask:0xf
	s_nop 1
	v_add_f32_dpp v37, v37, v37 quad_perm:[2,3,0,1] row_mask:0xf bank_mask:0xf
	s_nop 1
	v_add_f32_dpp v37, v37, v37 row_half_mirror row_mask:0xf bank_mask:0xf
	v_fmamk_f32 v38, v37, 0x3c800000, v225
	s_nop 0
	v_cmp_gt_f32_e64 s[2:3], s24, v38
	v_mul_f32_e32 v39, 0x4b800000, v38
	s_nop 0
	v_cndmask_b32_e64 v38, v38, v39, s[2:3]
	v_rsq_f32_e32 v38, v38
	s_nop 0
	v_mul_f32_e32 v39, 0x45800000, v38
	v_cndmask_b32_e64 v38, v38, v39, s[2:3]
	v_mul_f32_e32 v38, 0x3e000000, v38
	v_pk_mul_f32 v[0:1], v[0:1], v[38:39] op_sel_hi:[1,0]
	v_pk_mul_f32 v[2:3], v[2:3], v[38:39] op_sel_hi:[1,0]
	v_pk_mul_f32 v[4:5], v[4:5], v[38:39] op_sel_hi:[1,0]
	v_pk_mul_f32 v[6:7], v[6:7], v[38:39] op_sel_hi:[1,0]
	v_pk_mul_f32 v[0:1], v[0:1], v[40:41]
	v_pk_mul_f32 v[2:3], v[2:3], v[42:43]
	v_pk_mul_f32 v[4:5], v[4:5], v[44:45]
	v_pk_mul_f32 v[6:7], v[6:7], v[46:47]
	s_nop 0
	v_cvt_pk_bf16_f32 v48, v0, v1
	v_cvt_pk_bf16_f32 v49, v2, v3
	v_cvt_pk_bf16_f32 v50, v4, v5
	v_cvt_pk_bf16_f32 v51, v6, v7
	global_store_dwordx4 v35, v[48:51], s[62:63]
	global_load_dwordx4 v[40:43], v36, s[56:57]
	global_load_dwordx4 v[44:47], v36, s[56:57] offset:16
	global_load_dwordx4 v[60:63], v[30:31], off offset:1816
	global_load_dwordx4 v[64:67], v[32:33], off offset:1816
	global_load_dwordx4 v[68:71], v[30:31], off offset:1944
	global_load_dwordx4 v[72:75], v[32:33], off offset:1944
	global_load_dwordx4 v[76:79], v[30:31], off offset:2072
	global_load_dwordx4 v[8:11], v[32:33], off offset:2072
	global_load_dwordx4 v[12:15], v[30:31], off offset:2200
	global_load_dwordx4 v[48:51], v[32:33], off offset:2200
	s_waitcnt vmcnt(0)
; DI void prep_item(const Params& p, int L, int item, char* smem) {
;     ...
;   for (int jb = 0; jb < 44; jb += 4) {
;     u32x2 v0[4], v1[4];
; #pragma unroll
;     for (int u = 0; u < 4; ++u) {
;       const int job = (tid >> 3) + 32 * (jb + u);
;       const int tok = job & 63, vec = job >> 6;
;       int col;
;       if (vec < 4) col = 64 * vec; else if (vec < 8) col = 256 + 64 * (vec - 4); else if (vec < 12) col = 1964 + 64 * (vec - 8);
;       else if (vec < 16) col = 2220 + 64 * (vec - 12); else if (vec < 20) col = 1312 + 64 * (vec - 16); else if (vec == 20) col = 1696; else col = 1824;
;       const bfu* src = p.proj + (t0 + tok) * PJ + col + sub * 8;
;       v0[u] = *(const u32x2*)src; v1[u] = *(const u32x2*)(src + 4);
;     }
; #pragma unroll
;     for (int u = 0; u < 4; ++u) {
;       const int job = (tid >> 3) + 32 * (jb + u);
;       const int tok = job & 63, vec = job >> 6;
;       if ((vec < 8) ? (FUSE_MASK & 1) : (FUSE_MASK & 2)) continue;
;       const float* g = nullptr; float sc = 1.f; bfu* dst;
;       if (vec < 4)       { sc = 0.125f; dst = p.q_sb + (((size_t)(b * 4 + vec)) * S + s0 + tok) * 64; }
;       else if (vec < 8)  { int h = vec - 4; dst = p.k_sb + (((size_t)(b * 4 + h)) * S + s0 + tok) * 64; }
;       else if (vec < 12) { int h = vec - 8; g = p.fox_qn_g + L * 64; sc = 0.125f; dst = p.q_fox + (((size_t)(b * 4 + h)) * S + s0 + tok) * 64; }
;       else if (vec < 16) { int h = vec - 12; g = p.fox_kn_g + L * 64; dst = p.k_fox + (((size_t)(b * 4 + h)) * S + s0 + tok) * 64; }
;       else if (vec < 20) { int h = vec - 16; g = p.nsa_qn_g + L * 64; sc = 0.125f; dst = p.q_nsa + (((size_t)(b * 4 + h)) * S + s0 + tok) * 64; }
;       else if (vec == 20) { g = p.nsa_kn_g + (L * 3 + 1) * 64; dst = p.ks + ((size_t)b * S + s0 + tok) * 64; }
;       else               { g = p.nsa_kn_g + (L * 3 + 2) * 64; dst = p.kw + ((size_t)b * S + s0 + tok) * 64; }
;       float e[8] = {bflo(v0[u][0]), bfhi(v0[u][0]), bflo(v0[u][1]), bfhi(v0[u][1]), bflo(v1[u][0]), bfhi(v1[u][0]), bflo(v1[u][1]), bfhi(v1[u][1])};
;       float ss = 0.f;
; #pragma unroll
;       for (int q = 0; q < 8; ++q) ss += e[q] * e[q];
;       ss += __shfl_xor(ss, 1); ss += __shfl_xor(ss, 2); ss += __shfl_xor(ss, 4);
;       const float rs = g ? rsqrtf(ss * (1.f / 64.f) + EPS) * sc : sc;
; #pragma unroll
;       for (int q = 0; q < 8; ++q) e[q] = e[q] * rs * (g ? g[sub * 8 + q] : 1.f);
	v_lshlrev_b32_e32 v0, 16, v60
	v_and_b32_e32 v1, 0xffff0000, v60
	v_lshlrev_b32_e32 v2, 16, v61
	v_and_b32_e32 v3, 0xffff0000, v61
	v_lshlrev_b32_e32 v4, 16, v62
	v_and_b32_e32 v5, 0xffff0000, v62
	v_lshlrev_b32_e32 v6, 16, v63
	v_and_b32_e32 v7, 0xffff0000, v63
	v_mul_f32_e32 v37, v0, v0
	v_fmac_f32_e32 v37, v1, v1
	v_fmac_f32_e32 v37, v2, v2
	v_fmac_f32_e32 v37, v3, v3
	v_fmac_f32_e32 v37, v4, v4
	v_fmac_f32_e32 v37, v5, v5
	v_fmac_f32_e32 v37, v6, v6
	v_fmac_f32_e32 v37, v7, v7
	s_nop 1
	v_add_f32_dpp v37, v37, v37 quad_perm:[1,0,3,2] row_mask:0xf bank_mask:0xf
	s_nop 1
	v_add_f32_dpp v37, v37, v37 quad_perm:[2,3,0,1] row_mask:0xf bank_mask:0xf
	s_nop 1
	v_add_f32_dpp v37, v37, v37 row_half_mirror row_mask:0xf bank_mask:0xf
	v_fmamk_f32 v38, v37, 0x3c800000, v225
	s_nop 0
	v_cmp_gt_f32_e64 s[2:3], s24, v38
	v_mul_f32_e32 v39, 0x4b800000, v38
	s_nop 0
	v_cndmask_b32_e64 v38, v38, v39, s[2:3]
	v_rsq_f32_e32 v38, v38
	s_nop 0
	v_mul_f32_e32 v39, 0x45800000, v38
	v_cndmask_b32_e64 v38, v38, v39, s[2:3]
	v_pk_mul_f32 v[0:1], v[0:1], v[38:39] op_sel_hi:[1,0]
	v_pk_mul_f32 v[2:3], v[2:3], v[38:39] op_sel_hi:[1,0]
	v_pk_mul_f32 v[4:5], v[4:5], v[38:39] op_sel_hi:[1,0]
	v_pk_mul_f32 v[6:7], v[6:7], v[38:39] op_sel_hi:[1,0]
	v_pk_mul_f32 v[0:1], v[0:1], v[40:41]
	v_pk_mul_f32 v[2:3], v[2:3], v[42:43]
	v_pk_mul_f32 v[4:5], v[4:5], v[44:45]
	v_pk_mul_f32 v[6:7], v[6:7], v[46:47]
	s_nop 0
	v_cvt_pk_bf16_f32 v60, v0, v1
	v_cvt_pk_bf16_f32 v61, v2, v3
	v_cvt_pk_bf16_f32 v62, v4, v5
	v_cvt_pk_bf16_f32 v63, v6, v7
	global_store_dwordx4 v34, v[60:63], s[64:65]
	v_lshlrev_b32_e32 v0, 16, v64
	v_and_b32_e32 v1, 0xffff0000, v64
	v_lshlrev_b32_e32 v2, 16, v65
	v_and_b32_e32 v3, 0xffff0000, v65
	v_lshlrev_b32_e32 v4, 16, v66
	v_and_b32_e32 v5, 0xffff0000, v66
	v_lshlrev_b32_e32 v6, 16, v67
	v_and_b32_e32 v7, 0xffff0000, v67
	v_mul_f32_e32 v37, v0, v0
	v_fmac_f32_e32 v37, v1, v1
	v_fmac_f32_e32 v37, v2, v2
	v_fmac_f32_e32 v37, v3, v3
	v_fmac_f32_e32 v37, v4, v4
	v_fmac_f32_e32 v37, v5, v5
	v_fmac_f32_e32 v37, v6, v6
	v_fmac_f32_e32 v37, v7, v7
	s_nop 1
	v_add_f32_dpp v37, v37, v37 quad_perm:[1,0,3,2] row_mask:0xf bank_mask:0xf
	s_nop 1
	v_add_f32_dpp v37, v37, v37 quad_perm:[2,3,0,1] row_mask:0xf bank_mask:0xf
	s_nop 1
	v_add_f32_dpp v37, v37, v37 row_half_mirror row_mask:0xf bank_mask:0xf
	v_fmamk_f32 v38, v37, 0x3c800000, v225
	s_nop 0
	v_cmp_gt_f32_e64 s[2:3], s24, v38
	v_mul_f32_e32 v39, 0x4b800000, v38
	s_nop 0
	v_cndmask_b32_e64 v38, v38, v39, s[2:3]
	v_rsq_f32_e32 v38, v38
	s_nop 0
	v_mul_f32_e32 v39, 0x45800000, v38
	v_cndmask_b32_e64 v38, v38, v39, s[2:3]
	v_pk_mul_f32 v[0:1], v[0:1], v[38:39] op_sel_hi:[1,0]
	v_pk_mul_f32 v[2:3], v[2:3], v[38:39] op_sel_hi:[1,0]
	v_pk_mul_f32 v[4:5], v[4:5], v[38:39] op_sel_hi:[1,0]
	v_pk_mul_f32 v[6:7], v[6:7], v[38:39] op_sel_hi:[1,0]
	v_pk_mul_f32 v[0:1], v[0:1], v[40:41]
	v_pk_mul_f32 v[2:3], v[2:3], v[42:43]
	v_pk_mul_f32 v[4:5], v[4:5], v[44:45]
	v_pk_mul_f32 v[6:7], v[6:7], v[46:47]
	s_nop 0
	v_cvt_pk_bf16_f32 v64, v0, v1
	v_cvt_pk_bf16_f32 v65, v2, v3
	v_cvt_pk_bf16_f32 v66, v4, v5
	v_cvt_pk_bf16_f32 v67, v6, v7
	global_store_dwordx4 v35, v[64:67], s[64:65]
	s_add_u32 s64, s64, 0x40000
	s_addc_u32 s65, s65, 0
	v_lshlrev_b32_e32 v0, 16, v68
	v_and_b32_e32 v1, 0xffff0000, v68
	v_lshlrev_b32_e32 v2, 16, v69
	v_and_b32_e32 v3, 0xffff0000, v69
	v_lshlrev_b32_e32 v4, 16, v70
	v_and_b32_e32 v5, 0xffff0000, v70
	v_lshlrev_b32_e32 v6, 16, v71
	v_and_b32_e32 v7, 0xffff0000, v71
	v_mul_f32_e32 v37, v0, v0
	v_fmac_f32_e32 v37, v1, v1
	v_fmac_f32_e32 v37, v2, v2
	v_fmac_f32_e32 v37, v3, v3
	v_fmac_f32_e32 v37, v4, v4
	v_fmac_f32_e32 v37, v5, v5
	v_fmac_f32_e32 v37, v6, v6
	v_fmac_f32_e32 v37, v7, v7
	s_nop 1
	v_add_f32_dpp v37, v37, v37 quad_perm:[1,0,3,2] row_mask:0xf bank_mask:0xf
	s_nop 1
	v_add_f32_dpp v37, v37, v37 quad_perm:[2,3,0,1] row_mask:0xf bank_mask:0xf
	s_nop 1
	v_add_f32_dpp v37, v37, v37 row_half_mirror row_mask:0xf bank_mask:0xf
	v_fmamk_f32 v38, v37, 0x3c800000, v225
	s_nop 0
	v_cmp_gt_f32_e64 s[2:3], s24, v38
	v_mul_f32_e32 v39, 0x4b800000, v38
	s_nop 0
	v_cndmask_b32_e64 v38, v38, v39, s[2:3]
	v_rsq_f32_e32 v38, v38
	s_nop 0
	v_mul_f32_e32 v39, 0x45800000, v38
	v_cndmask_b32_e64 v38, v38, v39, s[2:3]
	v_pk_mul_f32 v[0:1], v[0:1], v[38:39] op_sel_hi:[1,0]
	v_pk_mul_f32 v[2:3], v[2:3], v[38:39] op_sel_hi:[1,0]
	v_pk_mul_f32 v[4:5], v[4:5], v[38:39] op_sel_hi:[1,0]
	v_pk_mul_f32 v[6:7], v[6:7], v[38:39] op_sel_hi:[1,0]
	v_pk_mul_f32 v[0:1], v[0:1], v[40:41]
	v_pk_mul_f32 v[2:3], v[2:3], v[42:43]
	v_pk_mul_f32 v[4:5], v[4:5], v[44:45]
	v_pk_mul_f32 v[6:7], v[6:7], v[46:47]
	s_nop 0
	v_cvt_pk_bf16_f32 v68, v0, v1
	v_cvt_pk_bf16_f32 v69, v2, v3
	v_cvt_pk_bf16_f32 v70, v4, v5
	v_cvt_pk_bf16_f32 v71, v6, v7
	global_store_dwordx4 v34, v[68:71], s[64:65]
	v_lshlrev_b32_e32 v0, 16, v72
	v_and_b32_e32 v1, 0xffff0000, v72
	v_lshlrev_b32_e32 v2, 16, v73
	v_and_b32_e32 v3, 0xffff0000, v73
	v_lshlrev_b32_e32 v4, 16, v74
	v_and_b32_e32 v5, 0xffff0000, v74
	v_lshlrev_b32_e32 v6, 16, v75
	v_and_b32_e32 v7, 0xffff0000, v75
	v_mul_f32_e32 v37, v0, v0
	v_fmac_f32_e32 v37, v1, v1
	v_fmac_f32_e32 v37, v2, v2
	v_fmac_f32_e32 v37, v3, v3
	v_fmac_f32_e32 v37, v4, v4
	v_fmac_f32_e32 v37, v5, v5
	v_fmac_f32_e32 v37, v6, v6
	v_fmac_f32_e32 v37, v7, v7
	s_nop 1
	v_add_f32_dpp v37, v37, v37 quad_perm:[1,0,3,2] row_mask:0xf bank_mask:0xf
	s_nop 1
	v_add_f32_dpp v37, v37, v37 quad_perm:[2,3,0,1] row_mask:0xf bank_mask:0xf
	s_nop 1
	v_add_f32_dpp v37, v37, v37 row_half_mirror row_mask:0xf bank_mask:0xf
	v_fmamk_f32 v38, v37, 0x3c800000, v225
	s_nop 0
	v_cmp_gt_f32_e64 s[2:3], s24, v38
	v_mul_f32_e32 v39, 0x4b800000, v38
	s_nop 0
; DI void prep_item(const Params& p, int L, int item, char* smem) {
;     ...
;   for (int jb = 0; jb < 44; jb += 4) {
;     u32x2 v0[4], v1[4];
; #pragma unroll
;     for (int u = 0; u < 4; ++u) {
;       const int job = (tid >> 3) + 32 * (jb + u);
;       const int tok = job & 63, vec = job >> 6;
;       int col;
;       if (vec < 4) col = 64 * vec; else if (vec < 8) col = 256 + 64 * (vec - 4); else if (vec < 12) col = 1964 + 64 * (vec - 8);
;       else if (vec < 16) col = 2220 + 64 * (vec - 12); else if (vec < 20) col = 1312 + 64 * (vec - 16); else if (vec == 20) col = 1696; else col = 1824;
;       const bfu* src = p.proj + (t0 + tok) * PJ + col + sub * 8;
;       v0[u] = *(const u32x2*)src; v1[u] = *(const u32x2*)(src + 4);
;     }
; #pragma unroll
;     for (int u = 0; u < 4; ++u) {
;       const int job = (tid >> 3) + 32 * (jb + u);
;       const int tok = job & 63, vec = job >> 6;
;       if ((vec < 8) ? (FUSE_MASK & 1) : (FUSE_MASK & 2)) continue;
;       const float* g = nullptr; float sc = 1.f; bfu* dst;
;       if (vec < 4)       { sc = 0.125f; dst = p.q_sb + (((size_t)(b * 4 + vec)) * S + s0 + tok) * 64; }
;       else if (vec < 8)  { int h = vec - 4; dst = p.k_sb + (((size_t)(b * 4 + h)) * S + s0 + tok) * 64; }
;       else if (vec < 12) { int h = vec - 8; g = p.fox_qn_g + L * 64; sc = 0.125f; dst = p.q_fox + (((size_t)(b * 4 + h)) * S + s0 + tok) * 64; }
;       else if (vec < 16) { int h = vec - 12; g = p.fox_kn_g + L * 64; dst = p.k_fox + (((size_t)(b * 4 + h)) * S + s0 + tok) * 64; }
;       else if (vec < 20) { int h = vec - 16; g = p.nsa_qn_g + L * 64; sc = 0.125f; dst = p.q_nsa + (((size_t)(b * 4 + h)) * S + s0 + tok) * 64; }
;       else if (vec == 20) { g = p.nsa_kn_g + (L * 3 + 1) * 64; dst = p.ks + ((size_t)b * S + s0 + tok) * 64; }
;       else               { g = p.nsa_kn_g + (L * 3 + 2) * 64; dst = p.kw + ((size_t)b * S + s0 + tok) * 64; }
;       float e[8] = {bflo(v0[u][0]), bfhi(v0[u][0]), bflo(v0[u][1]), bfhi(v0[u][1]), bflo(v1[u][0]), bfhi(v1[u][0]), bflo(v1[u][1]), bfhi(v1[u][1])};
;       float ss = 0.f;
; #pragma unroll
;       for (int q = 0; q < 8; ++q) ss += e[q] * e[q];
;       ss += __shfl_xor(ss, 1); ss += __shfl_xor(ss, 2); ss += __shfl_xor(ss, 4);
;       const float rs = g ? rsqrtf(ss * (1.f / 64.f) + EPS) * sc : sc;
; #pragma unroll
;       for (int q = 0; q < 8; ++q) e[q] = e[q] * rs * (g ? g[sub * 8 + q] : 1.f);
	v_cndmask_b32_e64 v38, v38, v39, s[2:3]
	v_rsq_f32_e32 v38, v38
	s_nop 0
	v_mul_f32_e32 v39, 0x45800000, v38
	v_cndmask_b32_e64 v38, v38, v39, s[2:3]
	v_pk_mul_f32 v[0:1], v[0:1], v[38:39] op_sel_hi:[1,0]
	v_pk_mul_f32 v[2:3], v[2:3], v[38:39] op_sel_hi:[1,0]
	v_pk_mul_f32 v[4:5], v[4:5], v[38:39] op_sel_hi:[1,0]
	v_pk_mul_f32 v[6:7], v[6:7], v[38:39] op_sel_hi:[1,0]
	v_pk_mul_f32 v[0:1], v[0:1], v[40:41]
	v_pk_mul_f32 v[2:3], v[2:3], v[42:43]
	v_pk_mul_f32 v[4:5], v[4:5], v[44:45]
	v_pk_mul_f32 v[6:7], v[6:7], v[46:47]
	s_nop 0
	v_cvt_pk_bf16_f32 v72, v0, v1
	v_cvt_pk_bf16_f32 v73, v2, v3
	v_cvt_pk_bf16_f32 v74, v4, v5
	v_cvt_pk_bf16_f32 v75, v6, v7
	global_store_dwordx4 v35, v[72:75], s[64:65]
	s_add_u32 s64, s64, 0x40000
	s_addc_u32 s65, s65, 0
	v_lshlrev_b32_e32 v0, 16, v76
	v_and_b32_e32 v1, 0xffff0000, v76
	v_lshlrev_b32_e32 v2, 16, v77
	v_and_b32_e32 v3, 0xffff0000, v77
	v_lshlrev_b32_e32 v4, 16, v78
	v_and_b32_e32 v5, 0xffff0000, v78
	v_lshlrev_b32_e32 v6, 16, v79
	v_and_b32_e32 v7, 0xffff0000, v79
	v_mul_f32_e32 v37, v0, v0
	v_fmac_f32_e32 v37, v1, v1
	v_fmac_f32_e32 v37, v2, v2
	v_fmac_f32_e32 v37, v3, v3
	v_fmac_f32_e32 v37, v4, v4
	v_fmac_f32_e32 v37, v5, v5
	v_fmac_f32_e32 v37, v6, v6
	v_fmac_f32_e32 v37, v7, v7
	s_nop 1
	v_add_f32_dpp v37, v37, v37 quad_perm:[1,0,3,2] row_mask:0xf bank_mask:0xf
	s_nop 1
	v_add_f32_dpp v37, v37, v37 quad_perm:[2,3,0,1] row_mask:0xf bank_mask:0xf
	s_nop 1
	v_add_f32_dpp v37, v37, v37 row_half_mirror row_mask:0xf bank_mask:0xf
	v_fmamk_f32 v38, v37, 0x3c800000, v225
	s_nop 0
	v_cmp_gt_f32_e64 s[2:3], s24, v38
	v_mul_f32_e32 v39, 0x4b800000, v38
	s_nop 0
	v_cndmask_b32_e64 v38, v38, v39, s[2:3]
	v_rsq_f32_e32 v38, v38
	s_nop 0
	v_mul_f32_e32 v39, 0x45800000, v38
	v_cndmask_b32_e64 v38, v38, v39, s[2:3]
	v_pk_mul_f32 v[0:1], v[0:1], v[38:39] op_sel_hi:[1,0]
	v_pk_mul_f32 v[2:3], v[2:3], v[38:39] op_sel_hi:[1,0]
	v_pk_mul_f32 v[4:5], v[4:5], v[38:39] op_sel_hi:[1,0]
	v_pk_mul_f32 v[6:7], v[6:7], v[38:39] op_sel_hi:[1,0]
	v_pk_mul_f32 v[0:1], v[0:1], v[40:41]
	v_pk_mul_f32 v[2:3], v[2:3], v[42:43]
	v_pk_mul_f32 v[4:5], v[4:5], v[44:45]
	v_pk_mul_f32 v[6:7], v[6:7], v[46:47]
	s_nop 0
	v_cvt_pk_bf16_f32 v76, v0, v1
	v_cvt_pk_bf16_f32 v77, v2, v3
	v_cvt_pk_bf16_f32 v78, v4, v5
	v_cvt_pk_bf16_f32 v79, v6, v7
	global_store_dwordx4 v34, v[76:79], s[64:65]
	v_lshlrev_b32_e32 v0, 16, v8
	v_and_b32_e32 v1, 0xffff0000, v8
	v_lshlrev_b32_e32 v2, 16, v9
	v_and_b32_e32 v3, 0xffff0000, v9
	v_lshlrev_b32_e32 v4, 16, v10
	v_and_b32_e32 v5, 0xffff0000, v10
	v_lshlrev_b32_e32 v6, 16, v11
	v_and_b32_e32 v7, 0xffff0000, v11
	v_mul_f32_e32 v37, v0, v0
	v_fmac_f32_e32 v37, v1, v1
	v_fmac_f32_e32 v37, v2, v2
	v_fmac_f32_e32 v37, v3, v3
	v_fmac_f32_e32 v37, v4, v4
	v_fmac_f32_e32 v37, v5, v5
	v_fmac_f32_e32 v37, v6, v6
	v_fmac_f32_e32 v37, v7, v7
	s_nop 1
	v_add_f32_dpp v37, v37, v37 quad_perm:[1,0,3,2] row_mask:0xf bank_mask:0xf
	s_nop 1
	v_add_f32_dpp v37, v37, v37 quad_perm:[2,3,0,1] row_mask:0xf bank_mask:0xf
	s_nop 1
	v_add_f32_dpp v37, v37, v37 row_half_mirror row_mask:0xf bank_mask:0xf
	v_fmamk_f32 v38, v37, 0x3c800000, v225
	s_nop 0
	v_cmp_gt_f32_e64 s[2:3], s24, v38
	v_mul_f32_e32 v39, 0x4b800000, v38
	s_nop 0
	v_cndmask_b32_e64 v38, v38, v39, s[2:3]
	v_rsq_f32_e32 v38, v38
	s_nop 0
	v_mul_f32_e32 v39, 0x45800000, v38
	v_cndmask_b32_e64 v38, v38, v39, s[2:3]
	v_pk_mul_f32 v[0:1], v[0:1], v[38:39] op_sel_hi:[1,0]
	v_pk_mul_f32 v[2:3], v[2:3], v[38:39] op_sel_hi:[1,0]
	v_pk_mul_f32 v[4:5], v[4:5], v[38:39] op_sel_hi:[1,0]
	v_pk_mul_f32 v[6:7], v[6:7], v[38:39] op_sel_hi:[1,0]
	v_pk_mul_f32 v[0:1], v[0:1], v[40:41]
	v_pk_mul_f32 v[2:3], v[2:3], v[42:43]
	v_pk_mul_f32 v[4:5], v[4:5], v[44:45]
	v_pk_mul_f32 v[6:7], v[6:7], v[46:47]
	s_nop 0
	v_cvt_pk_bf16_f32 v8, v0, v1
	v_cvt_pk_bf16_f32 v9, v2, v3
	v_cvt_pk_bf16_f32 v10, v4, v5
	v_cvt_pk_bf16_f32 v11, v6, v7
	global_store_dwordx4 v35, v[8:11], s[64:65]
	s_add_u32 s64, s64, 0x40000
	s_addc_u32 s65, s65, 0
	v_lshlrev_b32_e32 v0, 16, v12
	v_and_b32_e32 v1, 0xffff0000, v12
	v_lshlrev_b32_e32 v2, 16, v13
	v_and_b32_e32 v3, 0xffff0000, v13
	v_lshlrev_b32_e32 v4, 16, v14
	v_and_b32_e32 v5, 0xffff0000, v14
	v_lshlrev_b32_e32 v6, 16, v15
	v_and_b32_e32 v7, 0xffff0000, v15
	v_mul_f32_e32 v37, v0, v0
	v_fmac_f32_e32 v37, v1, v1
	v_fmac_f32_e32 v37, v2, v2
	v_fmac_f32_e32 v37, v3, v3
	v_fmac_f32_e32 v37, v4, v4
	v_fmac_f32_e32 v37, v5, v5
	v_fmac_f32_e32 v37, v6, v6
	v_fmac_f32_e32 v37, v7, v7
	s_nop 1
	v_add_f32_dpp v37, v37, v37 quad_perm:[1,0,3,2] row_mask:0xf bank_mask:0xf
	s_nop 1
	v_add_f32_dpp v37, v37, v37 quad_perm:[2,3,0,1] row_mask:0xf bank_mask:0xf
	s_nop 1
	v_add_f32_dpp v37, v37, v37 row_half_mirror row_mask:0xf bank_mask:0xf
	v_fmamk_f32 v38, v37, 0x3c800000, v225
	s_nop 0
	v_cmp_gt_f32_e64 s[2:3], s24, v38
	v_mul_f32_e32 v39, 0x4b800000, v38
	s_nop 0
	v_cndmask_b32_e64 v38, v38, v39, s[2:3]
	v_rsq_f32_e32 v38, v38
	s_nop 0
	v_mul_f32_e32 v39, 0x45800000, v38
	v_cndmask_b32_e64 v38, v38, v39, s[2:3]
	v_pk_mul_f32 v[0:1], v[0:1], v[38:39] op_sel_hi:[1,0]
	v_pk_mul_f32 v[2:3], v[2:3], v[38:39] op_sel_hi:[1,0]
	v_pk_mul_f32 v[4:5], v[4:5], v[38:39] op_sel_hi:[1,0]
	v_pk_mul_f32 v[6:7], v[6:7], v[38:39] op_sel_hi:[1,0]
	v_pk_mul_f32 v[0:1], v[0:1], v[40:41]
	v_pk_mul_f32 v[2:3], v[2:3], v[42:43]
	v_pk_mul_f32 v[4:5], v[4:5], v[44:45]
	v_pk_mul_f32 v[6:7], v[6:7], v[46:47]
	s_nop 0
	v_cvt_pk_bf16_f32 v12, v0, v1
	v_cvt_pk_bf16_f32 v13, v2, v3
	v_cvt_pk_bf16_f32 v14, v4, v5
	v_cvt_pk_bf16_f32 v15, v6, v7
	global_store_dwordx4 v34, v[12:15], s[64:65]
	v_lshlrev_b32_e32 v0, 16, v48
	v_and_b32_e32 v1, 0xffff0000, v48
	v_lshlrev_b32_e32 v2, 16, v49
	v_and_b32_e32 v3, 0xffff0000, v49
; DI void prep_item(const Params& p, int L, int item, char* smem) {
;     ...
;   for (int jb = 0; jb < 44; jb += 4) {
;     u32x2 v0[4], v1[4];
; #pragma unroll
;     for (int u = 0; u < 4; ++u) {
;       const int job = (tid >> 3) + 32 * (jb + u);
;       const int tok = job & 63, vec = job >> 6;
;       int col;
;       if (vec < 4) col = 64 * vec; else if (vec < 8) col = 256 + 64 * (vec - 4); else if (vec < 12) col = 1964 + 64 * (vec - 8);
;       else if (vec < 16) col = 2220 + 64 * (vec - 12); else if (vec < 20) col = 1312 + 64 * (vec - 16); else if (vec == 20) col = 1696; else col = 1824;
;       const bfu* src = p.proj + (t0 + tok) * PJ + col + sub * 8;
;       v0[u] = *(const u32x2*)src; v1[u] = *(const u32x2*)(src + 4);
;     }
; #pragma unroll
;     for (int u = 0; u < 4; ++u) {
;       const int job = (tid >> 3) + 32 * (jb + u);
;       const int tok = job & 63, vec = job >> 6;
;       if ((vec < 8) ? (FUSE_MASK & 1) : (FUSE_MASK & 2)) continue;
;       const float* g = nullptr; float sc = 1.f; bfu* dst;
;       if (vec < 4)       { sc = 0.125f; dst = p.q_sb + (((size_t)(b * 4 + vec)) * S + s0 + tok) * 64; }
;       else if (vec < 8)  { int h = vec - 4; dst = p.k_sb + (((size_t)(b * 4 + h)) * S + s0 + tok) * 64; }
;       else if (vec < 12) { int h = vec - 8; g = p.fox_qn_g + L * 64; sc = 0.125f; dst = p.q_fox + (((size_t)(b * 4 + h)) * S + s0 + tok) * 64; }
;       else if (vec < 16) { int h = vec - 12; g = p.fox_kn_g + L * 64; dst = p.k_fox + (((size_t)(b * 4 + h)) * S + s0 + tok) * 64; }
;       else if (vec < 20) { int h = vec - 16; g = p.nsa_qn_g + L * 64; sc = 0.125f; dst = p.q_nsa + (((size_t)(b * 4 + h)) * S + s0 + tok) * 64; }
;       else if (vec == 20) { g = p.nsa_kn_g + (L * 3 + 1) * 64; dst = p.ks + ((size_t)b * S + s0 + tok) * 64; }
;       else               { g = p.nsa_kn_g + (L * 3 + 2) * 64; dst = p.kw + ((size_t)b * S + s0 + tok) * 64; }
;       float e[8] = {bflo(v0[u][0]), bfhi(v0[u][0]), bflo(v0[u][1]), bfhi(v0[u][1]), bflo(v1[u][0]), bfhi(v1[u][0]), bflo(v1[u][1]), bfhi(v1[u][1])};
;       float ss = 0.f;
; #pragma unroll
;       for (int q = 0; q < 8; ++q) ss += e[q] * e[q];
;       ss += __shfl_xor(ss, 1); ss += __shfl_xor(ss, 2); ss += __shfl_xor(ss, 4);
;       const float rs = g ? rsqrtf(ss * (1.f / 64.f) + EPS) * sc : sc;
; #pragma unroll
;       for (int q = 0; q < 8; ++q) e[q] = e[q] * rs * (g ? g[sub * 8 + q] : 1.f);
	v_lshlrev_b32_e32 v4, 16, v50
	v_and_b32_e32 v5, 0xffff0000, v50
	v_lshlrev_b32_e32 v6, 16, v51
	v_and_b32_e32 v7, 0xffff0000, v51
	v_mul_f32_e32 v37, v0, v0
	v_fmac_f32_e32 v37, v1, v1
	v_fmac_f32_e32 v37, v2, v2
	v_fmac_f32_e32 v37, v3, v3
	v_fmac_f32_e32 v37, v4, v4
	v_fmac_f32_e32 v37, v5, v5
	v_fmac_f32_e32 v37, v6, v6
	v_fmac_f32_e32 v37, v7, v7
	s_nop 1
	v_add_f32_dpp v37, v37, v37 quad_perm:[1,0,3,2] row_mask:0xf bank_mask:0xf
	s_nop 1
	v_add_f32_dpp v37, v37, v37 quad_perm:[2,3,0,1] row_mask:0xf bank_mask:0xf
	s_nop 1
	v_add_f32_dpp v37, v37, v37 row_half_mirror row_mask:0xf bank_mask:0xf
	v_fmamk_f32 v38, v37, 0x3c800000, v225
	s_nop 0
	v_cmp_gt_f32_e64 s[2:3], s24, v38
	v_mul_f32_e32 v39, 0x4b800000, v38
	s_nop 0
	v_cndmask_b32_e64 v38, v38, v39, s[2:3]
	v_rsq_f32_e32 v38, v38
	s_nop 0
	v_mul_f32_e32 v39, 0x45800000, v38
	v_cndmask_b32_e64 v38, v38, v39, s[2:3]
	v_pk_mul_f32 v[0:1], v[0:1], v[38:39] op_sel_hi:[1,0]
	v_pk_mul_f32 v[2:3], v[2:3], v[38:39] op_sel_hi:[1,0]
	v_pk_mul_f32 v[4:5], v[4:5], v[38:39] op_sel_hi:[1,0]
	v_pk_mul_f32 v[6:7], v[6:7], v[38:39] op_sel_hi:[1,0]
	v_pk_mul_f32 v[0:1], v[0:1], v[40:41]
	v_pk_mul_f32 v[2:3], v[2:3], v[42:43]
	v_pk_mul_f32 v[4:5], v[4:5], v[44:45]
	v_pk_mul_f32 v[6:7], v[6:7], v[46:47]
	s_nop 0
	v_cvt_pk_bf16_f32 v48, v0, v1
	v_cvt_pk_bf16_f32 v49, v2, v3
	v_cvt_pk_bf16_f32 v50, v4, v5
	v_cvt_pk_bf16_f32 v51, v6, v7
	global_store_dwordx4 v35, v[48:51], s[64:65]
	global_load_dwordx4 v[40:43], v36, s[58:59]
	global_load_dwordx4 v[44:47], v36, s[58:59] offset:16
	global_load_dwordx4 v[60:63], v[30:31], off offset:0
	global_load_dwordx4 v[64:67], v[32:33], off offset:0
	global_load_dwordx4 v[68:71], v[30:31], off offset:128
	global_load_dwordx4 v[72:75], v[32:33], off offset:128
	global_load_dwordx4 v[76:79], v[30:31], off offset:256
	global_load_dwordx4 v[8:11], v[32:33], off offset:256
	global_load_dwordx4 v[12:15], v[30:31], off offset:384
	global_load_dwordx4 v[48:51], v[32:33], off offset:384
	s_waitcnt vmcnt(0)
	v_lshlrev_b32_e32 v0, 16, v60
	v_and_b32_e32 v1, 0xffff0000, v60
	v_lshlrev_b32_e32 v2, 16, v61
	v_and_b32_e32 v3, 0xffff0000, v61
	v_lshlrev_b32_e32 v4, 16, v62
	v_and_b32_e32 v5, 0xffff0000, v62
	v_lshlrev_b32_e32 v6, 16, v63
	v_and_b32_e32 v7, 0xffff0000, v63
	v_mul_f32_e32 v37, v0, v0
	v_fmac_f32_e32 v37, v1, v1
	v_fmac_f32_e32 v37, v2, v2
	v_fmac_f32_e32 v37, v3, v3
	v_fmac_f32_e32 v37, v4, v4
	v_fmac_f32_e32 v37, v5, v5
	v_fmac_f32_e32 v37, v6, v6
	v_fmac_f32_e32 v37, v7, v7
	s_nop 1
	v_add_f32_dpp v37, v37, v37 quad_perm:[1,0,3,2] row_mask:0xf bank_mask:0xf
	s_nop 1
	v_add_f32_dpp v37, v37, v37 quad_perm:[2,3,0,1] row_mask:0xf bank_mask:0xf
	s_nop 1
	v_add_f32_dpp v37, v37, v37 row_half_mirror row_mask:0xf bank_mask:0xf
	v_fmamk_f32 v38, v37, 0x3c800000, v225
	s_nop 0
	v_cmp_gt_f32_e64 s[2:3], s24, v38
	v_mul_f32_e32 v39, 0x4b800000, v38
	s_nop 0
	v_cndmask_b32_e64 v38, v38, v39, s[2:3]
	v_rsq_f32_e32 v38, v38
	s_nop 0
	v_mul_f32_e32 v39, 0x45800000, v38
	v_cndmask_b32_e64 v38, v38, v39, s[2:3]
	v_mul_f32_e32 v38, 0x3e000000, v38
	v_pk_mul_f32 v[0:1], v[0:1], v[38:39] op_sel_hi:[1,0]
	v_pk_mul_f32 v[2:3], v[2:3], v[38:39] op_sel_hi:[1,0]
	v_pk_mul_f32 v[4:5], v[4:5], v[38:39] op_sel_hi:[1,0]
	v_pk_mul_f32 v[6:7], v[6:7], v[38:39] op_sel_hi:[1,0]
	v_pk_mul_f32 v[0:1], v[0:1], v[40:41]
	v_pk_mul_f32 v[2:3], v[2:3], v[42:43]
	v_pk_mul_f32 v[4:5], v[4:5], v[44:45]
	v_pk_mul_f32 v[6:7], v[6:7], v[46:47]
	s_nop 0
	v_cvt_pk_bf16_f32 v60, v0, v1
	v_cvt_pk_bf16_f32 v61, v2, v3
	v_cvt_pk_bf16_f32 v62, v4, v5
	v_cvt_pk_bf16_f32 v63, v6, v7
	global_store_dwordx4 v34, v[60:63], s[66:67]
	v_lshlrev_b32_e32 v0, 16, v64
	v_and_b32_e32 v1, 0xffff0000, v64
	v_lshlrev_b32_e32 v2, 16, v65
	v_and_b32_e32 v3, 0xffff0000, v65
	v_lshlrev_b32_e32 v4, 16, v66
	v_and_b32_e32 v5, 0xffff0000, v66
	v_lshlrev_b32_e32 v6, 16, v67
	v_and_b32_e32 v7, 0xffff0000, v67
	v_mul_f32_e32 v37, v0, v0
	v_fmac_f32_e32 v37, v1, v1
	v_fmac_f32_e32 v37, v2, v2
	v_fmac_f32_e32 v37, v3, v3
	v_fmac_f32_e32 v37, v4, v4
	v_fmac_f32_e32 v37, v5, v5
	v_fmac_f32_e32 v37, v6, v6
	v_fmac_f32_e32 v37, v7, v7
	s_nop 1
	v_add_f32_dpp v37, v37, v37 quad_perm:[1,0,3,2] row_mask:0xf bank_mask:0xf
	s_nop 1
	v_add_f32_dpp v37, v37, v37 quad_perm:[2,3,0,1] row_mask:0xf bank_mask:0xf
	s_nop 1
	v_add_f32_dpp v37, v37, v37 row_half_mirror row_mask:0xf bank_mask:0xf
	v_fmamk_f32 v38, v37, 0x3c800000, v225
	s_nop 0
	v_cmp_gt_f32_e64 s[2:3], s24, v38
	v_mul_f32_e32 v39, 0x4b800000, v38
	s_nop 0
	v_cndmask_b32_e64 v38, v38, v39, s[2:3]
	v_rsq_f32_e32 v38, v38
	s_nop 0
	v_mul_f32_e32 v39, 0x45800000, v38
	v_cndmask_b32_e64 v38, v38, v39, s[2:3]
	v_mul_f32_e32 v38, 0x3e000000, v38
	v_pk_mul_f32 v[0:1], v[0:1], v[38:39] op_sel_hi:[1,0]
	v_pk_mul_f32 v[2:3], v[2:3], v[38:39] op_sel_hi:[1,0]
	v_pk_mul_f32 v[4:5], v[4:5], v[38:39] op_sel_hi:[1,0]
	v_pk_mul_f32 v[6:7], v[6:7], v[38:39] op_sel_hi:[1,0]
	v_pk_mul_f32 v[0:1], v[0:1], v[40:41]
	v_pk_mul_f32 v[2:3], v[2:3], v[42:43]
	v_pk_mul_f32 v[4:5], v[4:5], v[44:45]
	v_pk_mul_f32 v[6:7], v[6:7], v[46:47]
	s_nop 0
	v_cvt_pk_bf16_f32 v64, v0, v1
	v_cvt_pk_bf16_f32 v65, v2, v3
	v_cvt_pk_bf16_f32 v66, v4, v5
	v_cvt_pk_bf16_f32 v67, v6, v7
	global_store_dwordx4 v35, v[64:67], s[66:67]
	s_add_u32 s66, s66, 0x40000
	s_addc_u32 s67, s67, 0
	v_lshlrev_b32_e32 v0, 16, v68
	v_and_b32_e32 v1, 0xffff0000, v68
	v_lshlrev_b32_e32 v2, 16, v69
	v_and_b32_e32 v3, 0xffff0000, v69
	v_lshlrev_b32_e32 v4, 16, v70
	v_and_b32_e32 v5, 0xffff0000, v70
	v_lshlrev_b32_e32 v6, 16, v71
	v_and_b32_e32 v7, 0xffff0000, v71
	v_mul_f32_e32 v37, v0, v0
	v_fmac_f32_e32 v37, v1, v1
	v_fmac_f32_e32 v37, v2, v2
	v_fmac_f32_e32 v37, v3, v3
; DI void prep_item(const Params& p, int L, int item, char* smem) {
;     ...
;   for (int jb = 0; jb < 44; jb += 4) {
;     u32x2 v0[4], v1[4];
; #pragma unroll
;     for (int u = 0; u < 4; ++u) {
;       const int job = (tid >> 3) + 32 * (jb + u);
;       const int tok = job & 63, vec = job >> 6;
;       int col;
;       if (vec < 4) col = 64 * vec; else if (vec < 8) col = 256 + 64 * (vec - 4); else if (vec < 12) col = 1964 + 64 * (vec - 8);
;       else if (vec < 16) col = 2220 + 64 * (vec - 12); else if (vec < 20) col = 1312 + 64 * (vec - 16); else if (vec == 20) col = 1696; else col = 1824;
;       const bfu* src = p.proj + (t0 + tok) * PJ + col + sub * 8;
;       v0[u] = *(const u32x2*)src; v1[u] = *(const u32x2*)(src + 4);
;     }
; #pragma unroll
;     for (int u = 0; u < 4; ++u) {
;       const int job = (tid >> 3) + 32 * (jb + u);
;       const int tok = job & 63, vec = job >> 6;
;       if ((vec < 8) ? (FUSE_MASK & 1) : (FUSE_MASK & 2)) continue;
;       const float* g = nullptr; float sc = 1.f; bfu* dst;
;       if (vec < 4)       { sc = 0.125f; dst = p.q_sb + (((size_t)(b * 4 + vec)) * S + s0 + tok) * 64; }
;       else if (vec < 8)  { int h = vec - 4; dst = p.k_sb + (((size_t)(b * 4 + h)) * S + s0 + tok) * 64; }
;       else if (vec < 12) { int h = vec - 8; g = p.fox_qn_g + L * 64; sc = 0.125f; dst = p.q_fox + (((size_t)(b * 4 + h)) * S + s0 + tok) * 64; }
;       else if (vec < 16) { int h = vec - 12; g = p.fox_kn_g + L * 64; dst = p.k_fox + (((size_t)(b * 4 + h)) * S + s0 + tok) * 64; }
;       else if (vec < 20) { int h = vec - 16; g = p.nsa_qn_g + L * 64; sc = 0.125f; dst = p.q_nsa + (((size_t)(b * 4 + h)) * S + s0 + tok) * 64; }
;       else if (vec == 20) { g = p.nsa_kn_g + (L * 3 + 1) * 64; dst = p.ks + ((size_t)b * S + s0 + tok) * 64; }
;       else               { g = p.nsa_kn_g + (L * 3 + 2) * 64; dst = p.kw + ((size_t)b * S + s0 + tok) * 64; }
;       float e[8] = {bflo(v0[u][0]), bfhi(v0[u][0]), bflo(v0[u][1]), bfhi(v0[u][1]), bflo(v1[u][0]), bfhi(v1[u][0]), bflo(v1[u][1]), bfhi(v1[u][1])};
;       float ss = 0.f;
; #pragma unroll
;       for (int q = 0; q < 8; ++q) ss += e[q] * e[q];
;       ss += __shfl_xor(ss, 1); ss += __shfl_xor(ss, 2); ss += __shfl_xor(ss, 4);
;       const float rs = g ? rsqrtf(ss * (1.f / 64.f) + EPS) * sc : sc;
; #pragma unroll
;       for (int q = 0; q < 8; ++q) e[q] = e[q] * rs * (g ? g[sub * 8 + q] : 1.f);
	v_fmac_f32_e32 v37, v4, v4
	v_fmac_f32_e32 v37, v5, v5
	v_fmac_f32_e32 v37, v6, v6
	v_fmac_f32_e32 v37, v7, v7
	s_nop 1
	v_add_f32_dpp v37, v37, v37 quad_perm:[1,0,3,2] row_mask:0xf bank_mask:0xf
	s_nop 1
	v_add_f32_dpp v37, v37, v37 quad_perm:[2,3,0,1] row_mask:0xf bank_mask:0xf
	s_nop 1
	v_add_f32_dpp v37, v37, v37 row_half_mirror row_mask:0xf bank_mask:0xf
	v_fmamk_f32 v38, v37, 0x3c800000, v225
	s_nop 0
	v_cmp_gt_f32_e64 s[2:3], s24, v38
	v_mul_f32_e32 v39, 0x4b800000, v38
	s_nop 0
	v_cndmask_b32_e64 v38, v38, v39, s[2:3]
	v_rsq_f32_e32 v38, v38
	s_nop 0
	v_mul_f32_e32 v39, 0x45800000, v38
	v_cndmask_b32_e64 v38, v38, v39, s[2:3]
	v_mul_f32_e32 v38, 0x3e000000, v38
	v_pk_mul_f32 v[0:1], v[0:1], v[38:39] op_sel_hi:[1,0]
	v_pk_mul_f32 v[2:3], v[2:3], v[38:39] op_sel_hi:[1,0]
	v_pk_mul_f32 v[4:5], v[4:5], v[38:39] op_sel_hi:[1,0]
	v_pk_mul_f32 v[6:7], v[6:7], v[38:39] op_sel_hi:[1,0]
	v_pk_mul_f32 v[0:1], v[0:1], v[40:41]
	v_pk_mul_f32 v[2:3], v[2:3], v[42:43]
	v_pk_mul_f32 v[4:5], v[4:5], v[44:45]
	v_pk_mul_f32 v[6:7], v[6:7], v[46:47]
	s_nop 0
	v_cvt_pk_bf16_f32 v68, v0, v1
	v_cvt_pk_bf16_f32 v69, v2, v3
	v_cvt_pk_bf16_f32 v70, v4, v5
	v_cvt_pk_bf16_f32 v71, v6, v7
	global_store_dwordx4 v34, v[68:71], s[66:67]
	v_lshlrev_b32_e32 v0, 16, v72
	v_and_b32_e32 v1, 0xffff0000, v72
	v_lshlrev_b32_e32 v2, 16, v73
	v_and_b32_e32 v3, 0xffff0000, v73
	v_lshlrev_b32_e32 v4, 16, v74
	v_and_b32_e32 v5, 0xffff0000, v74
	v_lshlrev_b32_e32 v6, 16, v75
	v_and_b32_e32 v7, 0xffff0000, v75
	v_mul_f32_e32 v37, v0, v0
	v_fmac_f32_e32 v37, v1, v1
	v_fmac_f32_e32 v37, v2, v2
	v_fmac_f32_e32 v37, v3, v3
	v_fmac_f32_e32 v37, v4, v4
	v_fmac_f32_e32 v37, v5, v5
	v_fmac_f32_e32 v37, v6, v6
	v_fmac_f32_e32 v37, v7, v7
	s_nop 1
	v_add_f32_dpp v37, v37, v37 quad_perm:[1,0,3,2] row_mask:0xf bank_mask:0xf
	s_nop 1
	v_add_f32_dpp v37, v37, v37 quad_perm:[2,3,0,1] row_mask:0xf bank_mask:0xf
	s_nop 1
	v_add_f32_dpp v37, v37, v37 row_half_mirror row_mask:0xf bank_mask:0xf
	v_fmamk_f32 v38, v37, 0x3c800000, v225
	s_nop 0
	v_cmp_gt_f32_e64 s[2:3], s24, v38
	v_mul_f32_e32 v39, 0x4b800000, v38
	s_nop 0
	v_cndmask_b32_e64 v38, v38, v39, s[2:3]
	v_rsq_f32_e32 v38, v38
	s_nop 0
	v_mul_f32_e32 v39, 0x45800000, v38
	v_cndmask_b32_e64 v38, v38, v39, s[2:3]
	v_mul_f32_e32 v38, 0x3e000000, v38
	v_pk_mul_f32 v[0:1], v[0:1], v[38:39] op_sel_hi:[1,0]
	v_pk_mul_f32 v[2:3], v[2:3], v[38:39] op_sel_hi:[1,0]
	v_pk_mul_f32 v[4:5], v[4:5], v[38:39] op_sel_hi:[1,0]
	v_pk_mul_f32 v[6:7], v[6:7], v[38:39] op_sel_hi:[1,0]
	v_pk_mul_f32 v[0:1], v[0:1], v[40:41]
	v_pk_mul_f32 v[2:3], v[2:3], v[42:43]
	v_pk_mul_f32 v[4:5], v[4:5], v[44:45]
	v_pk_mul_f32 v[6:7], v[6:7], v[46:47]
	s_nop 0
	v_cvt_pk_bf16_f32 v72, v0, v1
	v_cvt_pk_bf16_f32 v73, v2, v3
	v_cvt_pk_bf16_f32 v74, v4, v5
	v_cvt_pk_bf16_f32 v75, v6, v7
	global_store_dwordx4 v35, v[72:75], s[66:67]
	s_add_u32 s66, s66, 0x40000
	s_addc_u32 s67, s67, 0
	v_lshlrev_b32_e32 v0, 16, v76
	v_and_b32_e32 v1, 0xffff0000, v76
	v_lshlrev_b32_e32 v2, 16, v77
	v_and_b32_e32 v3, 0xffff0000, v77
	v_lshlrev_b32_e32 v4, 16, v78
	v_and_b32_e32 v5, 0xffff0000, v78
	v_lshlrev_b32_e32 v6, 16, v79
	v_and_b32_e32 v7, 0xffff0000, v79
	v_mul_f32_e32 v37, v0, v0
	v_fmac_f32_e32 v37, v1, v1
	v_fmac_f32_e32 v37, v2, v2
	v_fmac_f32_e32 v37, v3, v3
	v_fmac_f32_e32 v37, v4, v4
	v_fmac_f32_e32 v37, v5, v5
	v_fmac_f32_e32 v37, v6, v6
	v_fmac_f32_e32 v37, v7, v7
	s_nop 1
	v_add_f32_dpp v37, v37, v37 quad_perm:[1,0,3,2] row_mask:0xf bank_mask:0xf
	s_nop 1
	v_add_f32_dpp v37, v37, v37 quad_perm:[2,3,0,1] row_mask:0xf bank_mask:0xf
	s_nop 1
	v_add_f32_dpp v37, v37, v37 row_half_mirror row_mask:0xf bank_mask:0xf
	v_fmamk_f32 v38, v37, 0x3c800000, v225
	s_nop 0
	v_cmp_gt_f32_e64 s[2:3], s24, v38
	v_mul_f32_e32 v39, 0x4b800000, v38
	s_nop 0
	v_cndmask_b32_e64 v38, v38, v39, s[2:3]
	v_rsq_f32_e32 v38, v38
	s_nop 0
	v_mul_f32_e32 v39, 0x45800000, v38
	v_cndmask_b32_e64 v38, v38, v39, s[2:3]
	v_mul_f32_e32 v38, 0x3e000000, v38
	v_pk_mul_f32 v[0:1], v[0:1], v[38:39] op_sel_hi:[1,0]
	v_pk_mul_f32 v[2:3], v[2:3], v[38:39] op_sel_hi:[1,0]
	v_pk_mul_f32 v[4:5], v[4:5], v[38:39] op_sel_hi:[1,0]
	v_pk_mul_f32 v[6:7], v[6:7], v[38:39] op_sel_hi:[1,0]
	v_pk_mul_f32 v[0:1], v[0:1], v[40:41]
	v_pk_mul_f32 v[2:3], v[2:3], v[42:43]
	v_pk_mul_f32 v[4:5], v[4:5], v[44:45]
	v_pk_mul_f32 v[6:7], v[6:7], v[46:47]
	s_nop 0
	v_cvt_pk_bf16_f32 v76, v0, v1
	v_cvt_pk_bf16_f32 v77, v2, v3
	v_cvt_pk_bf16_f32 v78, v4, v5
	v_cvt_pk_bf16_f32 v79, v6, v7
	global_store_dwordx4 v34, v[76:79], s[66:67]
	v_lshlrev_b32_e32 v0, 16, v8
	v_and_b32_e32 v1, 0xffff0000, v8
	v_lshlrev_b32_e32 v2, 16, v9
	v_and_b32_e32 v3, 0xffff0000, v9
	v_lshlrev_b32_e32 v4, 16, v10
	v_and_b32_e32 v5, 0xffff0000, v10
	v_lshlrev_b32_e32 v6, 16, v11
	v_and_b32_e32 v7, 0xffff0000, v11
	v_mul_f32_e32 v37, v0, v0
	v_fmac_f32_e32 v37, v1, v1
	v_fmac_f32_e32 v37, v2, v2
	v_fmac_f32_e32 v37, v3, v3
	v_fmac_f32_e32 v37, v4, v4
	v_fmac_f32_e32 v37, v5, v5
	v_fmac_f32_e32 v37, v6, v6
	v_fmac_f32_e32 v37, v7, v7
	s_nop 1
	v_add_f32_dpp v37, v37, v37 quad_perm:[1,0,3,2] row_mask:0xf bank_mask:0xf
	s_nop 1
	v_add_f32_dpp v37, v37, v37 quad_perm:[2,3,0,1] row_mask:0xf bank_mask:0xf
	s_nop 1
	v_add_f32_dpp v37, v37, v37 row_half_mirror row_mask:0xf bank_mask:0xf
	v_fmamk_f32 v38, v37, 0x3c800000, v225
	s_nop 0
	v_cmp_gt_f32_e64 s[2:3], s24, v38
	v_mul_f32_e32 v39, 0x4b800000, v38
	s_nop 0
	v_cndmask_b32_e64 v38, v38, v39, s[2:3]
	v_rsq_f32_e32 v38, v38
	s_nop 0
	v_mul_f32_e32 v39, 0x45800000, v38
	v_cndmask_b32_e64 v38, v38, v39, s[2:3]
	v_mul_f32_e32 v38, 0x3e000000, v38
	v_pk_mul_f32 v[0:1], v[0:1], v[38:39] op_sel_hi:[1,0]
	v_pk_mul_f32 v[2:3], v[2:3], v[38:39] op_sel_hi:[1,0]
; DI void prep_item(const Params& p, int L, int item, char* smem) {
;     ...
;   for (int jb = 0; jb < 44; jb += 4) {
;     u32x2 v0[4], v1[4];
; #pragma unroll
;     for (int u = 0; u < 4; ++u) {
;       const int job = (tid >> 3) + 32 * (jb + u);
;       const int tok = job & 63, vec = job >> 6;
;       int col;
;       if (vec < 4) col = 64 * vec; else if (vec < 8) col = 256 + 64 * (vec - 4); else if (vec < 12) col = 1964 + 64 * (vec - 8);
;       else if (vec < 16) col = 2220 + 64 * (vec - 12); else if (vec < 20) col = 1312 + 64 * (vec - 16); else if (vec == 20) col = 1696; else col = 1824;
;       const bfu* src = p.proj + (t0 + tok) * PJ + col + sub * 8;
;       v0[u] = *(const u32x2*)src; v1[u] = *(const u32x2*)(src + 4);
;     }
; #pragma unroll
;     for (int u = 0; u < 4; ++u) {
;       const int job = (tid >> 3) + 32 * (jb + u);
;       const int tok = job & 63, vec = job >> 6;
;       if ((vec < 8) ? (FUSE_MASK & 1) : (FUSE_MASK & 2)) continue;
;       const float* g = nullptr; float sc = 1.f; bfu* dst;
;       if (vec < 4)       { sc = 0.125f; dst = p.q_sb + (((size_t)(b * 4 + vec)) * S + s0 + tok) * 64; }
;       else if (vec < 8)  { int h = vec - 4; dst = p.k_sb + (((size_t)(b * 4 + h)) * S + s0 + tok) * 64; }
;       else if (vec < 12) { int h = vec - 8; g = p.fox_qn_g + L * 64; sc = 0.125f; dst = p.q_fox + (((size_t)(b * 4 + h)) * S + s0 + tok) * 64; }
;       else if (vec < 16) { int h = vec - 12; g = p.fox_kn_g + L * 64; dst = p.k_fox + (((size_t)(b * 4 + h)) * S + s0 + tok) * 64; }
;       else if (vec < 20) { int h = vec - 16; g = p.nsa_qn_g + L * 64; sc = 0.125f; dst = p.q_nsa + (((size_t)(b * 4 + h)) * S + s0 + tok) * 64; }
;       else if (vec == 20) { g = p.nsa_kn_g + (L * 3 + 1) * 64; dst = p.ks + ((size_t)b * S + s0 + tok) * 64; }
;       else               { g = p.nsa_kn_g + (L * 3 + 2) * 64; dst = p.kw + ((size_t)b * S + s0 + tok) * 64; }
;       float e[8] = {bflo(v0[u][0]), bfhi(v0[u][0]), bflo(v0[u][1]), bfhi(v0[u][1]), bflo(v1[u][0]), bfhi(v1[u][0]), bflo(v1[u][1]), bfhi(v1[u][1])};
;       float ss = 0.f;
; #pragma unroll
;       for (int q = 0; q < 8; ++q) ss += e[q] * e[q];
;       ss += __shfl_xor(ss, 1); ss += __shfl_xor(ss, 2); ss += __shfl_xor(ss, 4);
;       const float rs = g ? rsqrtf(ss * (1.f / 64.f) + EPS) * sc : sc;
; #pragma unroll
;       for (int q = 0; q < 8; ++q) e[q] = e[q] * rs * (g ? g[sub * 8 + q] : 1.f);
	v_pk_mul_f32 v[4:5], v[4:5], v[38:39] op_sel_hi:[1,0]
	v_pk_mul_f32 v[6:7], v[6:7], v[38:39] op_sel_hi:[1,0]
	v_pk_mul_f32 v[0:1], v[0:1], v[40:41]
	v_pk_mul_f32 v[2:3], v[2:3], v[42:43]
	v_pk_mul_f32 v[4:5], v[4:5], v[44:45]
	v_pk_mul_f32 v[6:7], v[6:7], v[46:47]
	s_nop 0
	v_cvt_pk_bf16_f32 v8, v0, v1
	v_cvt_pk_bf16_f32 v9, v2, v3
	v_cvt_pk_bf16_f32 v10, v4, v5
	v_cvt_pk_bf16_f32 v11, v6, v7
	global_store_dwordx4 v35, v[8:11], s[66:67]
	s_add_u32 s66, s66, 0x40000
	s_addc_u32 s67, s67, 0
	v_lshlrev_b32_e32 v0, 16, v12
	v_and_b32_e32 v1, 0xffff0000, v12
	v_lshlrev_b32_e32 v2, 16, v13
	v_and_b32_e32 v3, 0xffff0000, v13
	v_lshlrev_b32_e32 v4, 16, v14
	v_and_b32_e32 v5, 0xffff0000, v14
	v_lshlrev_b32_e32 v6, 16, v15
	v_and_b32_e32 v7, 0xffff0000, v15
	v_mul_f32_e32 v37, v0, v0
	v_fmac_f32_e32 v37, v1, v1
	v_fmac_f32_e32 v37, v2, v2
	v_fmac_f32_e32 v37, v3, v3
	v_fmac_f32_e32 v37, v4, v4
	v_fmac_f32_e32 v37, v5, v5
	v_fmac_f32_e32 v37, v6, v6
	v_fmac_f32_e32 v37, v7, v7
	s_nop 1
	v_add_f32_dpp v37, v37, v37 quad_perm:[1,0,3,2] row_mask:0xf bank_mask:0xf
	s_nop 1
	v_add_f32_dpp v37, v37, v37 quad_perm:[2,3,0,1] row_mask:0xf bank_mask:0xf
	s_nop 1
	v_add_f32_dpp v37, v37, v37 row_half_mirror row_mask:0xf bank_mask:0xf
	v_fmamk_f32 v38, v37, 0x3c800000, v225
	s_nop 0
	v_cmp_gt_f32_e64 s[2:3], s24, v38
	v_mul_f32_e32 v39, 0x4b800000, v38
	s_nop 0
	v_cndmask_b32_e64 v38, v38, v39, s[2:3]
	v_rsq_f32_e32 v38, v38
	s_nop 0
	v_mul_f32_e32 v39, 0x45800000, v38
	v_cndmask_b32_e64 v38, v38, v39, s[2:3]
	v_mul_f32_e32 v38, 0x3e000000, v38
	v_pk_mul_f32 v[0:1], v[0:1], v[38:39] op_sel_hi:[1,0]
	v_pk_mul_f32 v[2:3], v[2:3], v[38:39] op_sel_hi:[1,0]
	v_pk_mul_f32 v[4:5], v[4:5], v[38:39] op_sel_hi:[1,0]
	v_pk_mul_f32 v[6:7], v[6:7], v[38:39] op_sel_hi:[1,0]
	v_pk_mul_f32 v[0:1], v[0:1], v[40:41]
	v_pk_mul_f32 v[2:3], v[2:3], v[42:43]
	v_pk_mul_f32 v[4:5], v[4:5], v[44:45]
	v_pk_mul_f32 v[6:7], v[6:7], v[46:47]
	s_nop 0
	v_cvt_pk_bf16_f32 v12, v0, v1
	v_cvt_pk_bf16_f32 v13, v2, v3
	v_cvt_pk_bf16_f32 v14, v4, v5
	v_cvt_pk_bf16_f32 v15, v6, v7
	global_store_dwordx4 v34, v[12:15], s[66:67]
	v_lshlrev_b32_e32 v0, 16, v48
	v_and_b32_e32 v1, 0xffff0000, v48
	v_lshlrev_b32_e32 v2, 16, v49
	v_and_b32_e32 v3, 0xffff0000, v49
	v_lshlrev_b32_e32 v4, 16, v50
	v_and_b32_e32 v5, 0xffff0000, v50
	v_lshlrev_b32_e32 v6, 16, v51
	v_and_b32_e32 v7, 0xffff0000, v51
	v_mul_f32_e32 v37, v0, v0
	v_fmac_f32_e32 v37, v1, v1
	v_fmac_f32_e32 v37, v2, v2
	v_fmac_f32_e32 v37, v3, v3
	v_fmac_f32_e32 v37, v4, v4
	v_fmac_f32_e32 v37, v5, v5
	v_fmac_f32_e32 v37, v6, v6
	v_fmac_f32_e32 v37, v7, v7
	s_nop 1
	v_add_f32_dpp v37, v37, v37 quad_perm:[1,0,3,2] row_mask:0xf bank_mask:0xf
	s_nop 1
	v_add_f32_dpp v37, v37, v37 quad_perm:[2,3,0,1] row_mask:0xf bank_mask:0xf
	s_nop 1
	v_add_f32_dpp v37, v37, v37 row_half_mirror row_mask:0xf bank_mask:0xf
	v_fmamk_f32 v38, v37, 0x3c800000, v225
	s_nop 0
	v_cmp_gt_f32_e64 s[2:3], s24, v38
	v_mul_f32_e32 v39, 0x4b800000, v38
	s_nop 0
	v_cndmask_b32_e64 v38, v38, v39, s[2:3]
	v_rsq_f32_e32 v38, v38
	s_nop 0
	v_mul_f32_e32 v39, 0x45800000, v38
	v_cndmask_b32_e64 v38, v38, v39, s[2:3]
	v_mul_f32_e32 v38, 0x3e000000, v38
	v_pk_mul_f32 v[0:1], v[0:1], v[38:39] op_sel_hi:[1,0]
	v_pk_mul_f32 v[2:3], v[2:3], v[38:39] op_sel_hi:[1,0]
	v_pk_mul_f32 v[4:5], v[4:5], v[38:39] op_sel_hi:[1,0]
	v_pk_mul_f32 v[6:7], v[6:7], v[38:39] op_sel_hi:[1,0]
	v_pk_mul_f32 v[0:1], v[0:1], v[40:41]
	v_pk_mul_f32 v[2:3], v[2:3], v[42:43]
	v_pk_mul_f32 v[4:5], v[4:5], v[44:45]
	v_pk_mul_f32 v[6:7], v[6:7], v[46:47]
	s_nop 0
	v_cvt_pk_bf16_f32 v48, v0, v1
	v_cvt_pk_bf16_f32 v49, v2, v3
	v_cvt_pk_bf16_f32 v50, v4, v5
	v_cvt_pk_bf16_f32 v51, v6, v7
	global_store_dwordx4 v35, v[48:51], s[66:67]
	global_load_dwordx4 v[40:43], v36, s[60:61]
	global_load_dwordx4 v[44:47], v36, s[60:61] offset:16
	global_load_dwordx4 v[8:11], v36, s[60:61] offset:256
	global_load_dwordx4 v[12:15], v36, s[60:61] offset:272
	global_load_dwordx4 v[60:63], v[30:31], off offset:768
	global_load_dwordx4 v[64:67], v[32:33], off offset:768
	global_load_dwordx4 v[68:71], v[30:31], off offset:1024
	global_load_dwordx4 v[72:75], v[32:33], off offset:1024
	s_waitcnt vmcnt(0)
; DI unsigned pk2(float a, float b) { f32x2_t v = {a, b}; bf16x2_t r_ = __builtin_convertvector(v, bf16x2_t); return __builtin_bit_cast(unsigned, r_); }
; DI float bflo(unsigned u) { return __uint_as_float(u << 16); }
; DI float bfhi(unsigned u) { return __uint_as_float(u & 0xffff0000u); }
; DI void prep_item(const Params& p, int L, int item, char* smem) {
;     ...
;       const float* g = nullptr; float sc = 1.f; bfu* dst;
;       if (vec < 4)       { sc = 0.125f; dst = p.q_sb + (((size_t)(b * 4 + vec)) * S + s0 + tok) * 64; }
;       else if (vec < 8)  { int h = vec - 4; dst = p.k_sb + (((size_t)(b * 4 + h)) * S + s0 + tok) * 64; }
;       else if (vec < 12) { int h = vec - 8; g = p.fox_qn_g + L * 64; sc = 0.125f; dst = p.q_fox + (((size_t)(b * 4 + h)) * S + s0 + tok) * 64; }
;       else if (vec < 16) { int h = vec - 12; g = p.fox_kn_g + L * 64; dst = p.k_fox + (((size_t)(b * 4 + h)) * S + s0 + tok) * 64; }
;       else if (vec < 20) { int h = vec - 16; g = p.nsa_qn_g + L * 64; sc = 0.125f; dst = p.q_nsa + (((size_t)(b * 4 + h)) * S + s0 + tok) * 64; }
;       else if (vec == 20) { g = p.nsa_kn_g + (L * 3 + 1) * 64; dst = p.ks + ((size_t)b * S + s0 + tok) * 64; }
;       else               { g = p.nsa_kn_g + (L * 3 + 2) * 64; dst = p.kw + ((size_t)b * S + s0 + tok) * 64; }
;       float e[8] = {bflo(v0[u][0]), bfhi(v0[u][0]), bflo(v0[u][1]), bfhi(v0[u][1]), bflo(v1[u][0]), bfhi(v1[u][0]), bflo(v1[u][1]), bfhi(v1[u][1])};
;       float ss = 0.f;
; #pragma unroll
;       for (int q = 0; q < 8; ++q) ss += e[q] * e[q];
;       ss += __shfl_xor(ss, 1); ss += __shfl_xor(ss, 2); ss += __shfl_xor(ss, 4);
;       const float rs = g ? rsqrtf(ss * (1.f / 64.f) + EPS) * sc : sc;
; #pragma unroll
;       for (int q = 0; q < 8; ++q) e[q] = e[q] * rs * (g ? g[sub * 8 + q] : 1.f);
;       *(u32x4*)(dst + sub * 8) = (u32x4){pk2(e[0], e[1]), pk2(e[2], e[3]), pk2(e[4], e[5]), pk2(e[6], e[7])};
	v_lshlrev_b32_e32 v0, 16, v60
	v_and_b32_e32 v1, 0xffff0000, v60
	v_lshlrev_b32_e32 v2, 16, v61
	v_and_b32_e32 v3, 0xffff0000, v61
	v_lshlrev_b32_e32 v4, 16, v62
	v_and_b32_e32 v5, 0xffff0000, v62
	v_lshlrev_b32_e32 v6, 16, v63
	v_and_b32_e32 v7, 0xffff0000, v63
	v_mul_f32_e32 v37, v0, v0
	v_fmac_f32_e32 v37, v1, v1
	v_fmac_f32_e32 v37, v2, v2
	v_fmac_f32_e32 v37, v3, v3
	v_fmac_f32_e32 v37, v4, v4
	v_fmac_f32_e32 v37, v5, v5
	v_fmac_f32_e32 v37, v6, v6
	v_fmac_f32_e32 v37, v7, v7
	s_nop 1
	v_add_f32_dpp v37, v37, v37 quad_perm:[1,0,3,2] row_mask:0xf bank_mask:0xf
	s_nop 1
	v_add_f32_dpp v37, v37, v37 quad_perm:[2,3,0,1] row_mask:0xf bank_mask:0xf
	s_nop 1
	v_add_f32_dpp v37, v37, v37 row_half_mirror row_mask:0xf bank_mask:0xf
	v_fmamk_f32 v38, v37, 0x3c800000, v225
	s_nop 0
	v_cmp_gt_f32_e64 s[2:3], s24, v38
	v_mul_f32_e32 v39, 0x4b800000, v38
	s_nop 0
	v_cndmask_b32_e64 v38, v38, v39, s[2:3]
	v_rsq_f32_e32 v38, v38
	s_nop 0
	v_mul_f32_e32 v39, 0x45800000, v38
	v_cndmask_b32_e64 v38, v38, v39, s[2:3]
	v_pk_mul_f32 v[0:1], v[0:1], v[38:39] op_sel_hi:[1,0]
	v_pk_mul_f32 v[2:3], v[2:3], v[38:39] op_sel_hi:[1,0]
	v_pk_mul_f32 v[4:5], v[4:5], v[38:39] op_sel_hi:[1,0]
	v_pk_mul_f32 v[6:7], v[6:7], v[38:39] op_sel_hi:[1,0]
	v_pk_mul_f32 v[0:1], v[0:1], v[40:41]
	v_pk_mul_f32 v[2:3], v[2:3], v[42:43]
	v_pk_mul_f32 v[4:5], v[4:5], v[44:45]
	v_pk_mul_f32 v[6:7], v[6:7], v[46:47]
	s_nop 0
	v_cvt_pk_bf16_f32 v60, v0, v1
	v_cvt_pk_bf16_f32 v61, v2, v3
	v_cvt_pk_bf16_f32 v62, v4, v5
	v_cvt_pk_bf16_f32 v63, v6, v7
	global_store_dwordx4 v34, v[60:63], s[6:7]
	v_lshlrev_b32_e32 v0, 16, v64
	v_and_b32_e32 v1, 0xffff0000, v64
	v_lshlrev_b32_e32 v2, 16, v65
	v_and_b32_e32 v3, 0xffff0000, v65
	v_lshlrev_b32_e32 v4, 16, v66
	v_and_b32_e32 v5, 0xffff0000, v66
	v_lshlrev_b32_e32 v6, 16, v67
	v_and_b32_e32 v7, 0xffff0000, v67
	v_mul_f32_e32 v37, v0, v0
	v_fmac_f32_e32 v37, v1, v1
	v_fmac_f32_e32 v37, v2, v2
	v_fmac_f32_e32 v37, v3, v3
	v_fmac_f32_e32 v37, v4, v4
	v_fmac_f32_e32 v37, v5, v5
	v_fmac_f32_e32 v37, v6, v6
	v_fmac_f32_e32 v37, v7, v7
	s_nop 1
	v_add_f32_dpp v37, v37, v37 quad_perm:[1,0,3,2] row_mask:0xf bank_mask:0xf
	s_nop 1
	v_add_f32_dpp v37, v37, v37 quad_perm:[2,3,0,1] row_mask:0xf bank_mask:0xf
	s_nop 1
	v_add_f32_dpp v37, v37, v37 row_half_mirror row_mask:0xf bank_mask:0xf
	v_fmamk_f32 v38, v37, 0x3c800000, v225
	s_nop 0
	v_cmp_gt_f32_e64 s[2:3], s24, v38
	v_mul_f32_e32 v39, 0x4b800000, v38
	s_nop 0
	v_cndmask_b32_e64 v38, v38, v39, s[2:3]
	v_rsq_f32_e32 v38, v38
	s_nop 0
	v_mul_f32_e32 v39, 0x45800000, v38
	v_cndmask_b32_e64 v38, v38, v39, s[2:3]
	v_pk_mul_f32 v[0:1], v[0:1], v[38:39] op_sel_hi:[1,0]
	v_pk_mul_f32 v[2:3], v[2:3], v[38:39] op_sel_hi:[1,0]
	v_pk_mul_f32 v[4:5], v[4:5], v[38:39] op_sel_hi:[1,0]
	v_pk_mul_f32 v[6:7], v[6:7], v[38:39] op_sel_hi:[1,0]
	v_pk_mul_f32 v[0:1], v[0:1], v[40:41]
	v_pk_mul_f32 v[2:3], v[2:3], v[42:43]
	v_pk_mul_f32 v[4:5], v[4:5], v[44:45]
	v_pk_mul_f32 v[6:7], v[6:7], v[46:47]
	s_nop 0
	v_cvt_pk_bf16_f32 v64, v0, v1
	v_cvt_pk_bf16_f32 v65, v2, v3
	v_cvt_pk_bf16_f32 v66, v4, v5
	v_cvt_pk_bf16_f32 v67, v6, v7
	global_store_dwordx4 v35, v[64:67], s[6:7]
	v_lshlrev_b32_e32 v0, 16, v68
	v_and_b32_e32 v1, 0xffff0000, v68
	v_lshlrev_b32_e32 v2, 16, v69
	v_and_b32_e32 v3, 0xffff0000, v69
	v_lshlrev_b32_e32 v4, 16, v70
	v_and_b32_e32 v5, 0xffff0000, v70
	v_lshlrev_b32_e32 v6, 16, v71
	v_and_b32_e32 v7, 0xffff0000, v71
	v_mul_f32_e32 v37, v0, v0
	v_fmac_f32_e32 v37, v1, v1
	v_fmac_f32_e32 v37, v2, v2
	v_fmac_f32_e32 v37, v3, v3
	v_fmac_f32_e32 v37, v4, v4
	v_fmac_f32_e32 v37, v5, v5
	v_fmac_f32_e32 v37, v6, v6
	v_fmac_f32_e32 v37, v7, v7
	s_nop 1
	v_add_f32_dpp v37, v37, v37 quad_perm:[1,0,3,2] row_mask:0xf bank_mask:0xf
	s_nop 1
	v_add_f32_dpp v37, v37, v37 quad_perm:[2,3,0,1] row_mask:0xf bank_mask:0xf
	s_nop 1
	v_add_f32_dpp v37, v37, v37 row_half_mirror row_mask:0xf bank_mask:0xf
	v_fmamk_f32 v38, v37, 0x3c800000, v225
	s_nop 0
	v_cmp_gt_f32_e64 s[2:3], s24, v38
	v_mul_f32_e32 v39, 0x4b800000, v38
	s_nop 0
	v_cndmask_b32_e64 v38, v38, v39, s[2:3]
	v_rsq_f32_e32 v38, v38
	s_nop 0
	v_mul_f32_e32 v39, 0x45800000, v38
	v_cndmask_b32_e64 v38, v38, v39, s[2:3]
	v_pk_mul_f32 v[0:1], v[0:1], v[38:39] op_sel_hi:[1,0]
	v_pk_mul_f32 v[2:3], v[2:3], v[38:39] op_sel_hi:[1,0]
	v_pk_mul_f32 v[4:5], v[4:5], v[38:39] op_sel_hi:[1,0]
	v_pk_mul_f32 v[6:7], v[6:7], v[38:39] op_sel_hi:[1,0]
	v_pk_mul_f32 v[0:1], v[0:1], v[8:9]
	v_pk_mul_f32 v[2:3], v[2:3], v[10:11]
	v_pk_mul_f32 v[4:5], v[4:5], v[12:13]
	v_pk_mul_f32 v[6:7], v[6:7], v[14:15]
	s_nop 0
	v_cvt_pk_bf16_f32 v68, v0, v1
	v_cvt_pk_bf16_f32 v69, v2, v3
	v_cvt_pk_bf16_f32 v70, v4, v5
	v_cvt_pk_bf16_f32 v71, v6, v7
	global_store_dwordx4 v34, v[68:71], s[8:9]
	v_lshlrev_b32_e32 v0, 16, v72
	v_and_b32_e32 v1, 0xffff0000, v72
	v_lshlrev_b32_e32 v2, 16, v73
	v_and_b32_e32 v3, 0xffff0000, v73
	v_lshlrev_b32_e32 v4, 16, v74
	v_and_b32_e32 v5, 0xffff0000, v74
	v_lshlrev_b32_e32 v6, 16, v75
	v_and_b32_e32 v7, 0xffff0000, v75
	v_mul_f32_e32 v37, v0, v0
	v_fmac_f32_e32 v37, v1, v1
	v_fmac_f32_e32 v37, v2, v2
	v_fmac_f32_e32 v37, v3, v3
	v_fmac_f32_e32 v37, v4, v4
	v_fmac_f32_e32 v37, v5, v5
	v_fmac_f32_e32 v37, v6, v6
	v_fmac_f32_e32 v37, v7, v7
	s_nop 1
	v_add_f32_dpp v37, v37, v37 quad_perm:[1,0,3,2] row_mask:0xf bank_mask:0xf
	s_nop 1
	v_add_f32_dpp v37, v37, v37 quad_perm:[2,3,0,1] row_mask:0xf bank_mask:0xf
	s_nop 1
	v_add_f32_dpp v37, v37, v37 row_half_mirror row_mask:0xf bank_mask:0xf
	v_fmamk_f32 v38, v37, 0x3c800000, v225
	s_nop 0
	v_cmp_gt_f32_e64 s[2:3], s24, v38
	v_mul_f32_e32 v39, 0x4b800000, v38
	s_nop 0
	v_cndmask_b32_e64 v38, v38, v39, s[2:3]
	v_rsq_f32_e32 v38, v38
	s_nop 0
	v_mul_f32_e32 v39, 0x45800000, v38
	v_cndmask_b32_e64 v38, v38, v39, s[2:3]
	v_pk_mul_f32 v[0:1], v[0:1], v[38:39] op_sel_hi:[1,0]
	v_pk_mul_f32 v[2:3], v[2:3], v[38:39] op_sel_hi:[1,0]
	v_pk_mul_f32 v[4:5], v[4:5], v[38:39] op_sel_hi:[1,0]
	v_pk_mul_f32 v[6:7], v[6:7], v[38:39] op_sel_hi:[1,0]
	v_pk_mul_f32 v[0:1], v[0:1], v[8:9]
	v_pk_mul_f32 v[2:3], v[2:3], v[10:11]
	v_pk_mul_f32 v[4:5], v[4:5], v[12:13]
	v_pk_mul_f32 v[6:7], v[6:7], v[14:15]
	s_nop 0
	v_cvt_pk_bf16_f32 v72, v0, v1
	v_cvt_pk_bf16_f32 v73, v2, v3
	v_cvt_pk_bf16_f32 v74, v4, v5
	v_cvt_pk_bf16_f32 v75, v6, v7
	global_store_dwordx4 v35, v[72:75], s[8:9]
	s_branch .LBB0_731
